# scan consumer: next-step operand loads issued right after the pa chain instead of at the step head
# baseline (speedup 1.0000x reference)
.Lscan_cons_chunk:
	s_nop 0
	v_cndmask_b32_e64 v2, v4, v5, s[42:43]
	v_add_lshl_u32 v2, v2, s80, 10
	v_mov_b32_e64 v3, v180
	s_add_i32 s28, s28, 0x10000
	v_lshl_add_u64 v[2:3], v[0:1], 0, v[2:3]
	v_add_u32_e64 v5, 64, v5
	v_subrev_u32_e64 v4, 64, v4
	s_waitcnt lgkmcnt(0)
	s_nop 0
	v_fma_mix_f32 v12, v6, v20, v180 op_sel_hi:[0,1,0]
	v_fma_mix_f32 v12, v7, v20, v12 op_sel:[0,1,0] op_sel_hi:[0,1,0]
	v_fma_mix_f32 v12, v8, v21, v12 op_sel_hi:[0,1,0]
	v_fma_mix_f32 v12, v9, v21, v12 op_sel:[0,1,0] op_sel_hi:[0,1,0]
	ds_read_b128 v[88:91], v10 offset:2304
	ds_read_b128 v[96:99], v10 offset:2816
	ds_read_b128 v[92:95], v10 offset:2560
	s_nop 1
	s_nop 0
	v_add_f32_dpp v12, v12, v12 row_ror:1 row_mask:0xf bank_mask:0xf bound_ctrl:1
	s_nop 1
	s_nop 0
	v_add_f32_dpp v12, v12, v12 row_ror:2 row_mask:0xf bank_mask:0xf bound_ctrl:1
	v_pk_fma_f32 v[48:49], v[28:29], v[66:67], v[6:7] op_sel_hi:[1,0,1]
	v_pk_fma_f32 v[50:51], v[30:31], v[66:67], v[8:9] op_sel_hi:[1,0,1]
	v_add_f32_dpp v12, v12, v12 row_ror:4 row_mask:0xf bank_mask:0xf bound_ctrl:1
	v_add_f32_dpp v130, v130, v130 row_ror:8 row_mask:0xf bank_mask:0xc
	v_add_f32_dpp v130, v122, v122 row_ror:8 row_mask:0xf bank_mask:0x3
	v_add_f32_dpp v131, v131, v131 row_ror:8 row_mask:0xf bank_mask:0xc
	v_add_f32_dpp v12, v12, v12 row_ror:8 row_mask:0xf bank_mask:0xf bound_ctrl:1
	v_pk_fma_f32 v[6:7], v[24:25], v[12:13], v[48:49] op_sel_hi:[1,0,1] neg_lo:[1,0,0] neg_hi:[1,0,0]
	v_pk_fma_f32 v[8:9], v[26:27], v[12:13], v[50:51] op_sel_hi:[1,0,1] neg_lo:[1,0,0] neg_hi:[1,0,0]
	v_fma_mix_f32 v12, v6, v36, v180 op_sel_hi:[0,1,0]
	v_fma_mix_f32 v12, v7, v36, v12 op_sel:[0,1,0] op_sel_hi:[0,1,0]
	v_fma_mix_f32 v12, v8, v37, v12 op_sel_hi:[0,1,0]
	v_fma_mix_f32 v12, v9, v37, v12 op_sel:[0,1,0] op_sel_hi:[0,1,0]
	ds_read_b128 v[110:113], v10 offset:3328
	ds_read_b128 v[106:109], v10 offset:3072
	ds_read_b128 v[118:121], v10 offset:3840
	ds_read_b128 v[114:117], v10 offset:3584
	ds_read_b128 v[70:73], v11 offset:256
	v_fma_mix_f32 v52, v6, v22, v180 op_sel_hi:[0,1,0]
	v_fma_mix_f32 v52, v7, v22, v52 op_sel:[0,1,0] op_sel_hi:[0,1,0]
	v_add_f32_dpp v12, v12, v12 row_ror:1 row_mask:0xf bank_mask:0xf bound_ctrl:1
	v_fma_mix_f32 v52, v8, v23, v52 op_sel_hi:[0,1,0]
	v_fma_mix_f32 v52, v9, v23, v52 op_sel:[0,1,0] op_sel_hi:[0,1,0]
	v_add_f32_dpp v12, v12, v12 row_ror:2 row_mask:0xf bank_mask:0xf bound_ctrl:1
	v_pk_fma_f32 v[48:49], v[44:45], v[66:67], v[6:7] op_sel:[0,1,0]
	v_pk_fma_f32 v[50:51], v[46:47], v[66:67], v[8:9] op_sel:[0,1,0]
	v_add_f32_dpp v12, v12, v12 row_ror:4 row_mask:0xf bank_mask:0xf bound_ctrl:1
	v_add_f32_dpp v131, v123, v123 row_ror:8 row_mask:0xf bank_mask:0x3
	v_add_f32_dpp v132, v132, v132 row_ror:8 row_mask:0xf bank_mask:0xc
	v_add_f32_dpp v132, v124, v124 row_ror:8 row_mask:0xf bank_mask:0x3
	v_add_f32_dpp v12, v12, v12 row_ror:8 row_mask:0xf bank_mask:0xf bound_ctrl:1
	v_pk_fma_f32 v[6:7], v[40:41], v[12:13], v[48:49] op_sel_hi:[1,0,1] neg_lo:[1,0,0] neg_hi:[1,0,0]
	v_pk_fma_f32 v[8:9], v[42:43], v[12:13], v[50:51] op_sel_hi:[1,0,1] neg_lo:[1,0,0] neg_hi:[1,0,0]
	s_waitcnt lgkmcnt(1)
	s_nop 0
	v_fma_mix_f32 v12, v6, v88, v180 op_sel_hi:[0,1,0]
	v_fma_mix_f32 v12, v7, v88, v12 op_sel:[0,1,0] op_sel_hi:[0,1,0]
	v_fma_mix_f32 v12, v8, v89, v12 op_sel_hi:[0,1,0]
	v_fma_mix_f32 v12, v9, v89, v12 op_sel:[0,1,0] op_sel_hi:[0,1,0]
	ds_read_b128 v[20:23], v10 offset:4352
	ds_read_b128 v[28:31], v10 offset:4864
	ds_read_b128 v[24:27], v10 offset:4608
	v_fma_mix_f32 v53, v6, v38, v180 op_sel_hi:[0,1,0]
	v_fma_mix_f32 v53, v7, v38, v53 op_sel:[0,1,0] op_sel_hi:[0,1,0]
	v_add_f32_dpp v12, v12, v12 row_ror:1 row_mask:0xf bank_mask:0xf bound_ctrl:1
	v_fma_mix_f32 v53, v8, v39, v53 op_sel_hi:[0,1,0]
	v_fma_mix_f32 v53, v9, v39, v53 op_sel:[0,1,0] op_sel_hi:[0,1,0]
	v_add_f32_dpp v12, v12, v12 row_ror:2 row_mask:0xf bank_mask:0xf bound_ctrl:1
	v_pk_fma_f32 v[48:49], v[96:97], v[68:69], v[6:7] op_sel_hi:[1,0,1]
	v_pk_fma_f32 v[50:51], v[98:99], v[68:69], v[8:9] op_sel_hi:[1,0,1]
	v_add_f32_dpp v12, v12, v12 row_ror:4 row_mask:0xf bank_mask:0xf bound_ctrl:1
	v_add_f32_dpp v133, v133, v133 row_ror:8 row_mask:0xf bank_mask:0xc
	v_add_f32_dpp v133, v125, v125 row_ror:8 row_mask:0xf bank_mask:0x3
	v_add_f32_dpp v134, v134, v134 row_ror:8 row_mask:0xf bank_mask:0xc
	v_add_f32_dpp v12, v12, v12 row_ror:8 row_mask:0xf bank_mask:0xf bound_ctrl:1
	v_pk_fma_f32 v[6:7], v[92:93], v[12:13], v[48:49] op_sel_hi:[1,0,1] neg_lo:[1,0,0] neg_hi:[1,0,0]
	v_pk_fma_f32 v[8:9], v[94:95], v[12:13], v[50:51] op_sel_hi:[1,0,1] neg_lo:[1,0,0] neg_hi:[1,0,0]
	v_fma_mix_f32 v12, v6, v110, v180 op_sel_hi:[0,1,0]
	v_fma_mix_f32 v12, v7, v110, v12 op_sel:[0,1,0] op_sel_hi:[0,1,0]
	v_fma_mix_f32 v12, v8, v111, v12 op_sel_hi:[0,1,0]
	v_fma_mix_f32 v12, v9, v111, v12 op_sel:[0,1,0] op_sel_hi:[0,1,0]
	ds_read_b128 v[36:39], v10 offset:5376
	ds_read_b128 v[44:47], v10 offset:5888
	ds_read_b128 v[40:43], v10 offset:5632
	v_fma_mix_f32 v54, v6, v90, v180 op_sel_hi:[0,1,0]
	v_fma_mix_f32 v54, v7, v90, v54 op_sel:[0,1,0] op_sel_hi:[0,1,0]
	v_add_f32_dpp v12, v12, v12 row_ror:1 row_mask:0xf bank_mask:0xf bound_ctrl:1
	v_fma_mix_f32 v54, v8, v91, v54 op_sel_hi:[0,1,0]
	v_fma_mix_f32 v54, v9, v91, v54 op_sel:[0,1,0] op_sel_hi:[0,1,0]
	v_add_f32_dpp v12, v12, v12 row_ror:2 row_mask:0xf bank_mask:0xf bound_ctrl:1
	v_pk_fma_f32 v[48:49], v[118:119], v[68:69], v[6:7] op_sel:[0,1,0]
	v_pk_fma_f32 v[50:51], v[120:121], v[68:69], v[8:9] op_sel:[0,1,0]
	v_add_f32_dpp v12, v12, v12 row_ror:4 row_mask:0xf bank_mask:0xf bound_ctrl:1
	v_add_f32_dpp v134, v126, v126 row_ror:8 row_mask:0xf bank_mask:0x3
	v_add_f32_dpp v135, v135, v135 row_ror:8 row_mask:0xf bank_mask:0xc
	v_add_f32_dpp v135, v127, v127 row_ror:8 row_mask:0xf bank_mask:0x3
	v_add_f32_dpp v12, v12, v12 row_ror:8 row_mask:0xf bank_mask:0xf bound_ctrl:1
	v_pk_fma_f32 v[6:7], v[114:115], v[12:13], v[48:49] op_sel_hi:[1,0,1] neg_lo:[1,0,0] neg_hi:[1,0,0]
	v_pk_fma_f32 v[8:9], v[116:117], v[12:13], v[50:51] op_sel_hi:[1,0,1] neg_lo:[1,0,0] neg_hi:[1,0,0]
	v_pk_mul_f32 v[6:7], v[6:7], v[106:107]
	v_pk_mul_f32 v[8:9], v[8:9], v[108:109]
	s_waitcnt lgkmcnt(0)
	s_nop 0
	v_fma_mix_f32 v12, v6, v20, v180 op_sel_hi:[0,1,0]
	v_fma_mix_f32 v12, v7, v20, v12 op_sel:[0,1,0] op_sel_hi:[0,1,0]
	v_fma_mix_f32 v12, v8, v21, v12 op_sel_hi:[0,1,0]
	v_fma_mix_f32 v12, v9, v21, v12 op_sel:[0,1,0] op_sel_hi:[0,1,0]
	ds_read_b128 v[88:91], v10 offset:6400
	ds_read_b128 v[96:99], v10 offset:6912
	ds_read_b128 v[92:95], v10 offset:6656
	v_fma_mix_f32 v55, v6, v112, v180 op_sel_hi:[0,1,0]
	v_fma_mix_f32 v55, v7, v112, v55 op_sel:[0,1,0] op_sel_hi:[0,1,0]
	v_add_f32_dpp v12, v12, v12 row_ror:1 row_mask:0xf bank_mask:0xf bound_ctrl:1
	v_fma_mix_f32 v55, v8, v113, v55 op_sel_hi:[0,1,0]
	v_fma_mix_f32 v55, v9, v113, v55 op_sel:[0,1,0] op_sel_hi:[0,1,0]
	v_add_f32_dpp v12, v12, v12 row_ror:2 row_mask:0xf bank_mask:0xf bound_ctrl:1
	v_pk_fma_f32 v[48:49], v[28:29], v[70:71], v[6:7] op_sel_hi:[1,0,1]
	v_pk_fma_f32 v[50:51], v[30:31], v[70:71], v[8:9] op_sel_hi:[1,0,1]
	v_add_f32_dpp v12, v12, v12 row_ror:4 row_mask:0xf bank_mask:0xf bound_ctrl:1
	v_add_f32_dpp v136, v136, v136 row_ror:8 row_mask:0xf bank_mask:0xc
	v_add_f32_dpp v136, v128, v128 row_ror:8 row_mask:0xf bank_mask:0x3
	v_add_f32_dpp v12, v12, v12 row_ror:8 row_mask:0xf bank_mask:0xf bound_ctrl:1
	v_pk_fma_f32 v[6:7], v[24:25], v[12:13], v[48:49] op_sel_hi:[1,0,1] neg_lo:[1,0,0] neg_hi:[1,0,0]
	v_pk_fma_f32 v[8:9], v[26:27], v[12:13], v[50:51] op_sel_hi:[1,0,1] neg_lo:[1,0,0] neg_hi:[1,0,0]
	v_fma_mix_f32 v12, v6, v36, v180 op_sel_hi:[0,1,0]
	v_fma_mix_f32 v12, v7, v36, v12 op_sel:[0,1,0] op_sel_hi:[0,1,0]
	v_fma_mix_f32 v12, v8, v37, v12 op_sel_hi:[0,1,0]
	v_fma_mix_f32 v12, v9, v37, v12 op_sel:[0,1,0] op_sel_hi:[0,1,0]
	ds_read_b128 v[110:113], v10 offset:7424
	ds_read_b128 v[106:109], v10 offset:7168
	ds_read_b128 v[118:121], v10 offset:7936
	ds_read_b128 v[114:117], v10 offset:7680
	ds_read_b128 v[66:69], v11 offset:512
	v_fma_mix_f32 v56, v6, v22, v180 op_sel_hi:[0,1,0]
	v_fma_mix_f32 v56, v7, v22, v56 op_sel:[0,1,0] op_sel_hi:[0,1,0]
	v_add_f32_dpp v12, v12, v12 row_ror:1 row_mask:0xf bank_mask:0xf bound_ctrl:1
	v_fma_mix_f32 v56, v8, v23, v56 op_sel_hi:[0,1,0]
	v_fma_mix_f32 v56, v9, v23, v56 op_sel:[0,1,0] op_sel_hi:[0,1,0]
	v_add_f32_dpp v12, v12, v12 row_ror:2 row_mask:0xf bank_mask:0xf bound_ctrl:1
	v_pk_fma_f32 v[48:49], v[44:45], v[70:71], v[6:7] op_sel:[0,1,0]
	v_pk_fma_f32 v[50:51], v[46:47], v[70:71], v[8:9] op_sel:[0,1,0]
	v_add_f32_dpp v12, v12, v12 row_ror:4 row_mask:0xf bank_mask:0xf bound_ctrl:1
	v_add_f32_dpp v137, v137, v137 row_ror:8 row_mask:0xf bank_mask:0xc
	v_add_f32_dpp v137, v129, v129 row_ror:8 row_mask:0xf bank_mask:0x3
	v_add_f32_dpp v12, v12, v12 row_ror:8 row_mask:0xf bank_mask:0xf bound_ctrl:1
	v_pk_fma_f32 v[6:7], v[40:41], v[12:13], v[48:49] op_sel_hi:[1,0,1] neg_lo:[1,0,0] neg_hi:[1,0,0]
	v_pk_fma_f32 v[8:9], v[42:43], v[12:13], v[50:51] op_sel_hi:[1,0,1] neg_lo:[1,0,0] neg_hi:[1,0,0]
	s_waitcnt lgkmcnt(1)
	s_nop 0
	v_fma_mix_f32 v12, v6, v88, v180 op_sel_hi:[0,1,0]
	v_fma_mix_f32 v12, v7, v88, v12 op_sel:[0,1,0] op_sel_hi:[0,1,0]
	v_fma_mix_f32 v12, v8, v89, v12 op_sel_hi:[0,1,0]
	v_fma_mix_f32 v12, v9, v89, v12 op_sel:[0,1,0] op_sel_hi:[0,1,0]
	ds_read_b128 v[20:23], v10 offset:8448
	ds_read_b128 v[28:31], v10 offset:8960
	ds_read_b128 v[24:27], v10 offset:8704
	v_fma_mix_f32 v57, v6, v38, v180 op_sel_hi:[0,1,0]
	v_fma_mix_f32 v57, v7, v38, v57 op_sel:[0,1,0] op_sel_hi:[0,1,0]
	v_add_f32_dpp v12, v12, v12 row_ror:1 row_mask:0xf bank_mask:0xf bound_ctrl:1
	v_fma_mix_f32 v57, v8, v39, v57 op_sel_hi:[0,1,0]
	v_fma_mix_f32 v57, v9, v39, v57 op_sel:[0,1,0] op_sel_hi:[0,1,0]
	v_add_f32_dpp v12, v12, v12 row_ror:2 row_mask:0xf bank_mask:0xf bound_ctrl:1
	v_pk_fma_f32 v[48:49], v[96:97], v[72:73], v[6:7] op_sel_hi:[1,0,1]
	v_pk_fma_f32 v[50:51], v[98:99], v[72:73], v[8:9] op_sel_hi:[1,0,1]
	v_add_f32_dpp v12, v12, v12 row_ror:4 row_mask:0xf bank_mask:0xf bound_ctrl:1
	v_add_f32_dpp v134, v134, v134 row_ror:4 row_mask:0xf bank_mask:0xa
	v_add_f32_dpp v134, v130, v130 row_ror:12 row_mask:0xf bank_mask:0x5
	v_add_f32_dpp v135, v135, v135 row_ror:4 row_mask:0xf bank_mask:0xa
	v_add_f32_dpp v12, v12, v12 row_ror:8 row_mask:0xf bank_mask:0xf bound_ctrl:1
	v_pk_fma_f32 v[6:7], v[92:93], v[12:13], v[48:49] op_sel_hi:[1,0,1] neg_lo:[1,0,0] neg_hi:[1,0,0]
	v_pk_fma_f32 v[8:9], v[94:95], v[12:13], v[50:51] op_sel_hi:[1,0,1] neg_lo:[1,0,0] neg_hi:[1,0,0]
	v_fma_mix_f32 v12, v6, v110, v180 op_sel_hi:[0,1,0]
	v_fma_mix_f32 v12, v7, v110, v12 op_sel:[0,1,0] op_sel_hi:[0,1,0]
	v_fma_mix_f32 v12, v8, v111, v12 op_sel_hi:[0,1,0]
	v_fma_mix_f32 v12, v9, v111, v12 op_sel:[0,1,0] op_sel_hi:[0,1,0]
	ds_read_b128 v[36:39], v10 offset:9472
	ds_read_b128 v[44:47], v10 offset:9984
	ds_read_b128 v[40:43], v10 offset:9728
	v_fma_mix_f32 v81, v6, v90, v180 op_sel_hi:[0,1,0]
	v_fma_mix_f32 v81, v7, v90, v81 op_sel:[0,1,0] op_sel_hi:[0,1,0]
	v_add_f32_dpp v12, v12, v12 row_ror:1 row_mask:0xf bank_mask:0xf bound_ctrl:1
	v_fma_mix_f32 v81, v8, v91, v81 op_sel_hi:[0,1,0]
	v_fma_mix_f32 v81, v9, v91, v81 op_sel:[0,1,0] op_sel_hi:[0,1,0]
	v_add_f32_dpp v12, v12, v12 row_ror:2 row_mask:0xf bank_mask:0xf bound_ctrl:1
	v_pk_fma_f32 v[48:49], v[118:119], v[72:73], v[6:7] op_sel:[0,1,0]
	v_pk_fma_f32 v[50:51], v[120:121], v[72:73], v[8:9] op_sel:[0,1,0]
	v_add_f32_dpp v12, v12, v12 row_ror:4 row_mask:0xf bank_mask:0xf bound_ctrl:1
	v_add_f32_dpp v135, v131, v131 row_ror:12 row_mask:0xf bank_mask:0x5
	v_add_f32_dpp v136, v136, v136 row_ror:4 row_mask:0xf bank_mask:0xa
	v_add_f32_dpp v136, v132, v132 row_ror:12 row_mask:0xf bank_mask:0x5
	v_add_f32_dpp v12, v12, v12 row_ror:8 row_mask:0xf bank_mask:0xf bound_ctrl:1
	v_pk_fma_f32 v[6:7], v[114:115], v[12:13], v[48:49] op_sel_hi:[1,0,1] neg_lo:[1,0,0] neg_hi:[1,0,0]
	v_pk_fma_f32 v[8:9], v[116:117], v[12:13], v[50:51] op_sel_hi:[1,0,1] neg_lo:[1,0,0] neg_hi:[1,0,0]
	v_pk_mul_f32 v[6:7], v[6:7], v[106:107]
	v_pk_mul_f32 v[8:9], v[8:9], v[108:109]
	s_waitcnt lgkmcnt(0)
	s_nop 0
	v_fma_mix_f32 v12, v6, v20, v180 op_sel_hi:[0,1,0]
	v_fma_mix_f32 v12, v7, v20, v12 op_sel:[0,1,0] op_sel_hi:[0,1,0]
	v_fma_mix_f32 v12, v8, v21, v12 op_sel_hi:[0,1,0]
	v_fma_mix_f32 v12, v9, v21, v12 op_sel:[0,1,0] op_sel_hi:[0,1,0]
	ds_read_b128 v[88:91], v10 offset:10496
	ds_read_b128 v[96:99], v10 offset:11008
	ds_read_b128 v[92:95], v10 offset:10752
	v_fma_mix_f32 v82, v6, v112, v180 op_sel_hi:[0,1,0]
	v_fma_mix_f32 v82, v7, v112, v82 op_sel:[0,1,0] op_sel_hi:[0,1,0]
	v_add_f32_dpp v12, v12, v12 row_ror:1 row_mask:0xf bank_mask:0xf bound_ctrl:1
	v_fma_mix_f32 v82, v8, v113, v82 op_sel_hi:[0,1,0]
	v_fma_mix_f32 v82, v9, v113, v82 op_sel:[0,1,0] op_sel_hi:[0,1,0]
	v_add_f32_dpp v12, v12, v12 row_ror:2 row_mask:0xf bank_mask:0xf bound_ctrl:1
	v_pk_fma_f32 v[48:49], v[28:29], v[66:67], v[6:7] op_sel_hi:[1,0,1]
	v_pk_fma_f32 v[50:51], v[30:31], v[66:67], v[8:9] op_sel_hi:[1,0,1]
	v_add_f32_dpp v12, v12, v12 row_ror:4 row_mask:0xf bank_mask:0xf bound_ctrl:1
	v_add_f32_dpp v137, v137, v137 row_ror:4 row_mask:0xf bank_mask:0xa
	v_add_f32_dpp v137, v133, v133 row_ror:12 row_mask:0xf bank_mask:0x5
	v_add_f32_dpp v12, v12, v12 row_ror:8 row_mask:0xf bank_mask:0xf bound_ctrl:1
	v_pk_fma_f32 v[6:7], v[24:25], v[12:13], v[48:49] op_sel_hi:[1,0,1] neg_lo:[1,0,0] neg_hi:[1,0,0]
	v_pk_fma_f32 v[8:9], v[26:27], v[12:13], v[50:51] op_sel_hi:[1,0,1] neg_lo:[1,0,0] neg_hi:[1,0,0]
	v_fma_mix_f32 v12, v6, v36, v180 op_sel_hi:[0,1,0]
	v_fma_mix_f32 v12, v7, v36, v12 op_sel:[0,1,0] op_sel_hi:[0,1,0]
	v_fma_mix_f32 v12, v8, v37, v12 op_sel_hi:[0,1,0]
	v_fma_mix_f32 v12, v9, v37, v12 op_sel:[0,1,0] op_sel_hi:[0,1,0]
	ds_read_b128 v[110:113], v10 offset:11520
	ds_read_b128 v[106:109], v10 offset:11264
	ds_read_b128 v[118:121], v10 offset:12032
	ds_read_b128 v[114:117], v10 offset:11776
	ds_read_b128 v[70:73], v11 offset:768
	v_fma_mix_f32 v83, v6, v22, v180 op_sel_hi:[0,1,0]
	v_fma_mix_f32 v83, v7, v22, v83 op_sel:[0,1,0] op_sel_hi:[0,1,0]
	v_add_f32_dpp v12, v12, v12 row_ror:1 row_mask:0xf bank_mask:0xf bound_ctrl:1
	v_fma_mix_f32 v83, v8, v23, v83 op_sel_hi:[0,1,0]
	v_fma_mix_f32 v83, v9, v23, v83 op_sel:[0,1,0] op_sel_hi:[0,1,0]
	v_add_f32_dpp v12, v12, v12 row_ror:2 row_mask:0xf bank_mask:0xf bound_ctrl:1
	v_pk_fma_f32 v[48:49], v[44:45], v[66:67], v[6:7] op_sel:[0,1,0]
	v_pk_fma_f32 v[50:51], v[46:47], v[66:67], v[8:9] op_sel:[0,1,0]
	v_add_f32_dpp v12, v12, v12 row_ror:4 row_mask:0xf bank_mask:0xf bound_ctrl:1
	v_cndmask_b32_e64 v62, v136, v134, s[38:39]
	v_cndmask_b32_e64 v63, v134, v136, s[38:39]
	v_add_f32_dpp v12, v12, v12 row_ror:8 row_mask:0xf bank_mask:0xf bound_ctrl:1
	v_pk_fma_f32 v[6:7], v[40:41], v[12:13], v[48:49] op_sel_hi:[1,0,1] neg_lo:[1,0,0] neg_hi:[1,0,0]
	v_pk_fma_f32 v[8:9], v[42:43], v[12:13], v[50:51] op_sel_hi:[1,0,1] neg_lo:[1,0,0] neg_hi:[1,0,0]
	s_waitcnt lgkmcnt(1)
	s_nop 0
	v_fma_mix_f32 v12, v6, v88, v180 op_sel_hi:[0,1,0]
	v_fma_mix_f32 v12, v7, v88, v12 op_sel:[0,1,0] op_sel_hi:[0,1,0]
	v_fma_mix_f32 v12, v8, v89, v12 op_sel_hi:[0,1,0]
	v_fma_mix_f32 v12, v9, v89, v12 op_sel:[0,1,0] op_sel_hi:[0,1,0]
	ds_read_b128 v[20:23], v10 offset:12544
	ds_read_b128 v[28:31], v10 offset:13056
	ds_read_b128 v[24:27], v10 offset:12800
	v_fma_mix_f32 v100, v6, v38, v180 op_sel_hi:[0,1,0]
	v_fma_mix_f32 v100, v7, v38, v100 op_sel:[0,1,0] op_sel_hi:[0,1,0]
	v_add_f32_dpp v12, v12, v12 row_ror:1 row_mask:0xf bank_mask:0xf bound_ctrl:1
	v_fma_mix_f32 v100, v8, v39, v100 op_sel_hi:[0,1,0]
	v_fma_mix_f32 v100, v9, v39, v100 op_sel:[0,1,0] op_sel_hi:[0,1,0]
	v_add_f32_dpp v12, v12, v12 row_ror:2 row_mask:0xf bank_mask:0xf bound_ctrl:1
	v_pk_fma_f32 v[48:49], v[96:97], v[68:69], v[6:7] op_sel_hi:[1,0,1]
	v_pk_fma_f32 v[50:51], v[98:99], v[68:69], v[8:9] op_sel_hi:[1,0,1]
	v_add_f32_dpp v12, v12, v12 row_ror:4 row_mask:0xf bank_mask:0xf bound_ctrl:1
	v_cndmask_b32_e64 v64, v137, v135, s[38:39]
	v_cndmask_b32_e64 v65, v135, v137, s[38:39]
	v_add_f32_dpp v12, v12, v12 row_ror:8 row_mask:0xf bank_mask:0xf bound_ctrl:1
	v_pk_fma_f32 v[6:7], v[92:93], v[12:13], v[48:49] op_sel_hi:[1,0,1] neg_lo:[1,0,0] neg_hi:[1,0,0]
	v_pk_fma_f32 v[8:9], v[94:95], v[12:13], v[50:51] op_sel_hi:[1,0,1] neg_lo:[1,0,0] neg_hi:[1,0,0]
	v_fma_mix_f32 v12, v6, v110, v180 op_sel_hi:[0,1,0]
	v_fma_mix_f32 v12, v7, v110, v12 op_sel:[0,1,0] op_sel_hi:[0,1,0]
	v_fma_mix_f32 v12, v8, v111, v12 op_sel_hi:[0,1,0]
	v_fma_mix_f32 v12, v9, v111, v12 op_sel:[0,1,0] op_sel_hi:[0,1,0]
	ds_read_b128 v[36:39], v10 offset:13568
	ds_read_b128 v[44:47], v10 offset:14080
	ds_read_b128 v[40:43], v10 offset:13824
	v_fma_mix_f32 v101, v6, v90, v180 op_sel_hi:[0,1,0]
	v_fma_mix_f32 v101, v7, v90, v101 op_sel:[0,1,0] op_sel_hi:[0,1,0]
	v_add_f32_dpp v12, v12, v12 row_ror:1 row_mask:0xf bank_mask:0xf bound_ctrl:1
	v_fma_mix_f32 v101, v8, v91, v101 op_sel_hi:[0,1,0]
	v_fma_mix_f32 v101, v9, v91, v101 op_sel:[0,1,0] op_sel_hi:[0,1,0]
	v_add_f32_dpp v12, v12, v12 row_ror:2 row_mask:0xf bank_mask:0xf bound_ctrl:1
	v_pk_fma_f32 v[48:49], v[118:119], v[68:69], v[6:7] op_sel:[0,1,0]
	v_pk_fma_f32 v[50:51], v[120:121], v[68:69], v[8:9] op_sel:[0,1,0]
	v_add_f32_dpp v12, v12, v12 row_ror:4 row_mask:0xf bank_mask:0xf bound_ctrl:1
	v_add_f32_dpp v62, v63, v62 quad_perm:[2,3,0,1] row_mask:0xf bank_mask:0xf bound_ctrl:1
	v_add_f32_dpp v63, v65, v64 quad_perm:[2,3,0,1] row_mask:0xf bank_mask:0xf bound_ctrl:1
	v_add_f32_dpp v12, v12, v12 row_ror:8 row_mask:0xf bank_mask:0xf bound_ctrl:1
	v_pk_fma_f32 v[6:7], v[114:115], v[12:13], v[48:49] op_sel_hi:[1,0,1] neg_lo:[1,0,0] neg_hi:[1,0,0]
	v_pk_fma_f32 v[8:9], v[116:117], v[12:13], v[50:51] op_sel_hi:[1,0,1] neg_lo:[1,0,0] neg_hi:[1,0,0]
	v_pk_mul_f32 v[6:7], v[6:7], v[106:107]
	v_pk_mul_f32 v[8:9], v[8:9], v[108:109]
	s_waitcnt lgkmcnt(0)
	s_nop 0
	v_fma_mix_f32 v12, v6, v20, v180 op_sel_hi:[0,1,0]
	v_fma_mix_f32 v12, v7, v20, v12 op_sel:[0,1,0] op_sel_hi:[0,1,0]
	v_fma_mix_f32 v12, v8, v21, v12 op_sel_hi:[0,1,0]
	v_fma_mix_f32 v12, v9, v21, v12 op_sel:[0,1,0] op_sel_hi:[0,1,0]
	ds_read_b128 v[88:91], v10 offset:14592
	ds_read_b128 v[96:99], v10 offset:15104
	ds_read_b128 v[92:95], v10 offset:14848
	v_fma_mix_f32 v102, v6, v112, v180 op_sel_hi:[0,1,0]
	v_fma_mix_f32 v102, v7, v112, v102 op_sel:[0,1,0] op_sel_hi:[0,1,0]
	v_add_f32_dpp v12, v12, v12 row_ror:1 row_mask:0xf bank_mask:0xf bound_ctrl:1
	v_fma_mix_f32 v102, v8, v113, v102 op_sel_hi:[0,1,0]
	v_fma_mix_f32 v102, v9, v113, v102 op_sel:[0,1,0] op_sel_hi:[0,1,0]
	v_add_f32_dpp v12, v12, v12 row_ror:2 row_mask:0xf bank_mask:0xf bound_ctrl:1
	v_pk_fma_f32 v[48:49], v[28:29], v[70:71], v[6:7] op_sel_hi:[1,0,1]
	v_pk_fma_f32 v[50:51], v[30:31], v[70:71], v[8:9] op_sel_hi:[1,0,1]
	v_add_f32_dpp v12, v12, v12 row_ror:4 row_mask:0xf bank_mask:0xf bound_ctrl:1
	v_cndmask_b32_e64 v65, v63, v62, s[40:41]
	v_cndmask_b32_e64 v62, v62, v63, s[40:41]
	v_add_f32_dpp v12, v12, v12 row_ror:8 row_mask:0xf bank_mask:0xf bound_ctrl:1
	v_pk_fma_f32 v[6:7], v[24:25], v[12:13], v[48:49] op_sel_hi:[1,0,1] neg_lo:[1,0,0] neg_hi:[1,0,0]
	v_pk_fma_f32 v[8:9], v[26:27], v[12:13], v[50:51] op_sel_hi:[1,0,1] neg_lo:[1,0,0] neg_hi:[1,0,0]
	v_fma_mix_f32 v12, v6, v36, v180 op_sel_hi:[0,1,0]
	v_fma_mix_f32 v12, v7, v36, v12 op_sel:[0,1,0] op_sel_hi:[0,1,0]
	v_fma_mix_f32 v12, v8, v37, v12 op_sel_hi:[0,1,0]
	v_fma_mix_f32 v12, v9, v37, v12 op_sel:[0,1,0] op_sel_hi:[0,1,0]
	ds_read_b128 v[110:113], v10 offset:15616
	ds_read_b128 v[106:109], v10 offset:15360
	ds_read_b128 v[118:121], v10 offset:16128
	ds_read_b128 v[114:117], v10 offset:15872
	ds_read_b128 v[66:69], v11 offset:1024
	v_fma_mix_f32 v103, v6, v22, v180 op_sel_hi:[0,1,0]
	v_fma_mix_f32 v103, v7, v22, v103 op_sel:[0,1,0] op_sel_hi:[0,1,0]
	v_add_f32_dpp v12, v12, v12 row_ror:1 row_mask:0xf bank_mask:0xf bound_ctrl:1
	v_fma_mix_f32 v103, v8, v23, v103 op_sel_hi:[0,1,0]
	v_fma_mix_f32 v103, v9, v23, v103 op_sel:[0,1,0] op_sel_hi:[0,1,0]
	v_add_f32_dpp v12, v12, v12 row_ror:2 row_mask:0xf bank_mask:0xf bound_ctrl:1
	v_pk_fma_f32 v[48:49], v[44:45], v[70:71], v[6:7] op_sel:[0,1,0]
	v_pk_fma_f32 v[50:51], v[46:47], v[70:71], v[8:9] op_sel:[0,1,0]
	v_add_f32_dpp v12, v12, v12 row_ror:4 row_mask:0xf bank_mask:0xf bound_ctrl:1
	v_add_f32_dpp v62, v62, v65 quad_perm:[1,0,3,2] row_mask:0xf bank_mask:0xf bound_ctrl:1
	v_cvt_pk_bf16_f32 v62, v62, v62
	v_add_f32_dpp v12, v12, v12 row_ror:8 row_mask:0xf bank_mask:0xf bound_ctrl:1
	v_pk_fma_f32 v[6:7], v[40:41], v[12:13], v[48:49] op_sel_hi:[1,0,1] neg_lo:[1,0,0] neg_hi:[1,0,0]
	v_pk_fma_f32 v[8:9], v[42:43], v[12:13], v[50:51] op_sel_hi:[1,0,1] neg_lo:[1,0,0] neg_hi:[1,0,0]
	s_waitcnt lgkmcnt(1)
	s_nop 0
	v_fma_mix_f32 v12, v6, v88, v180 op_sel_hi:[0,1,0]
	v_fma_mix_f32 v12, v7, v88, v12 op_sel:[0,1,0] op_sel_hi:[0,1,0]
	v_fma_mix_f32 v12, v8, v89, v12 op_sel_hi:[0,1,0]
	v_fma_mix_f32 v12, v9, v89, v12 op_sel:[0,1,0] op_sel_hi:[0,1,0]
	ds_read_b128 v[20:23], v10 offset:16640
	ds_read_b128 v[28:31], v10 offset:17152
	ds_read_b128 v[24:27], v10 offset:16896
	v_fma_mix_f32 v104, v6, v38, v180 op_sel_hi:[0,1,0]
	v_fma_mix_f32 v104, v7, v38, v104 op_sel:[0,1,0] op_sel_hi:[0,1,0]
	v_add_f32_dpp v12, v12, v12 row_ror:1 row_mask:0xf bank_mask:0xf bound_ctrl:1
	v_fma_mix_f32 v104, v8, v39, v104 op_sel_hi:[0,1,0]
	v_fma_mix_f32 v104, v9, v39, v104 op_sel:[0,1,0] op_sel_hi:[0,1,0]
	v_add_f32_dpp v12, v12, v12 row_ror:2 row_mask:0xf bank_mask:0xf bound_ctrl:1
	v_pk_fma_f32 v[48:49], v[96:97], v[72:73], v[6:7] op_sel_hi:[1,0,1]
	v_pk_fma_f32 v[50:51], v[98:99], v[72:73], v[8:9] op_sel_hi:[1,0,1]
	v_add_f32_dpp v12, v12, v12 row_ror:4 row_mask:0xf bank_mask:0xf bound_ctrl:1
	s_mov_b64 exec, s[100:101]
	s_nop 0
	global_store_short v[170:171], v62, off
	s_mov_b64 exec, -1
	s_nop 0
	v_add_f32_dpp v12, v12, v12 row_ror:8 row_mask:0xf bank_mask:0xf bound_ctrl:1
	v_pk_fma_f32 v[6:7], v[92:93], v[12:13], v[48:49] op_sel_hi:[1,0,1] neg_lo:[1,0,0] neg_hi:[1,0,0]
	v_pk_fma_f32 v[8:9], v[94:95], v[12:13], v[50:51] op_sel_hi:[1,0,1] neg_lo:[1,0,0] neg_hi:[1,0,0]
	v_fma_mix_f32 v12, v6, v110, v180 op_sel_hi:[0,1,0]
	v_fma_mix_f32 v12, v7, v110, v12 op_sel:[0,1,0] op_sel_hi:[0,1,0]
	v_fma_mix_f32 v12, v8, v111, v12 op_sel_hi:[0,1,0]
	v_fma_mix_f32 v12, v9, v111, v12 op_sel:[0,1,0] op_sel_hi:[0,1,0]
	ds_read_b128 v[36:39], v10 offset:17664
	ds_read_b128 v[44:47], v10 offset:18176
	ds_read_b128 v[40:43], v10 offset:17920
	v_fma_mix_f32 v105, v6, v90, v180 op_sel_hi:[0,1,0]
	v_fma_mix_f32 v105, v7, v90, v105 op_sel:[0,1,0] op_sel_hi:[0,1,0]
	v_add_f32_dpp v12, v12, v12 row_ror:1 row_mask:0xf bank_mask:0xf bound_ctrl:1
	v_fma_mix_f32 v105, v8, v91, v105 op_sel_hi:[0,1,0]
	v_fma_mix_f32 v105, v9, v91, v105 op_sel:[0,1,0] op_sel_hi:[0,1,0]
	v_add_f32_dpp v12, v12, v12 row_ror:2 row_mask:0xf bank_mask:0xf bound_ctrl:1
	v_pk_fma_f32 v[48:49], v[118:119], v[72:73], v[6:7] op_sel:[0,1,0]
	v_pk_fma_f32 v[50:51], v[120:121], v[72:73], v[8:9] op_sel:[0,1,0]
	v_add_f32_dpp v12, v12, v12 row_ror:4 row_mask:0xf bank_mask:0xf bound_ctrl:1
	s_nop 1
	s_nop 0
	v_add_f32_dpp v12, v12, v12 row_ror:8 row_mask:0xf bank_mask:0xf bound_ctrl:1
	v_pk_fma_f32 v[6:7], v[114:115], v[12:13], v[48:49] op_sel_hi:[1,0,1] neg_lo:[1,0,0] neg_hi:[1,0,0]
	v_pk_fma_f32 v[8:9], v[116:117], v[12:13], v[50:51] op_sel_hi:[1,0,1] neg_lo:[1,0,0] neg_hi:[1,0,0]
	v_pk_mul_f32 v[6:7], v[6:7], v[106:107]
	v_pk_mul_f32 v[8:9], v[8:9], v[108:109]
	s_waitcnt lgkmcnt(0)
	s_nop 0
	v_fma_mix_f32 v12, v6, v20, v180 op_sel_hi:[0,1,0]
	v_fma_mix_f32 v12, v7, v20, v12 op_sel:[0,1,0] op_sel_hi:[0,1,0]
	v_fma_mix_f32 v12, v8, v21, v12 op_sel_hi:[0,1,0]
	v_fma_mix_f32 v12, v9, v21, v12 op_sel:[0,1,0] op_sel_hi:[0,1,0]
	ds_read_b128 v[88:91], v10 offset:18688
	ds_read_b128 v[96:99], v10 offset:19200
	ds_read_b128 v[92:95], v10 offset:18944
	v_fma_mix_f32 v61, v6, v112, v180 op_sel_hi:[0,1,0]
	v_fma_mix_f32 v61, v7, v112, v61 op_sel:[0,1,0] op_sel_hi:[0,1,0]
	v_add_f32_dpp v12, v12, v12 row_ror:1 row_mask:0xf bank_mask:0xf bound_ctrl:1
	v_fma_mix_f32 v61, v8, v113, v61 op_sel_hi:[0,1,0]
	v_fma_mix_f32 v61, v9, v113, v61 op_sel:[0,1,0] op_sel_hi:[0,1,0]
	v_add_f32_dpp v12, v12, v12 row_ror:2 row_mask:0xf bank_mask:0xf bound_ctrl:1
	v_pk_fma_f32 v[48:49], v[28:29], v[66:67], v[6:7] op_sel_hi:[1,0,1]
	v_pk_fma_f32 v[50:51], v[30:31], v[66:67], v[8:9] op_sel_hi:[1,0,1]
	v_add_f32_dpp v12, v12, v12 row_ror:4 row_mask:0xf bank_mask:0xf bound_ctrl:1
	s_nop 1
	s_nop 0
	v_add_f32_dpp v12, v12, v12 row_ror:8 row_mask:0xf bank_mask:0xf bound_ctrl:1
	v_pk_fma_f32 v[6:7], v[24:25], v[12:13], v[48:49] op_sel_hi:[1,0,1] neg_lo:[1,0,0] neg_hi:[1,0,0]
	v_pk_fma_f32 v[8:9], v[26:27], v[12:13], v[50:51] op_sel_hi:[1,0,1] neg_lo:[1,0,0] neg_hi:[1,0,0]
	v_fma_mix_f32 v12, v6, v36, v180 op_sel_hi:[0,1,0]
	v_fma_mix_f32 v12, v7, v36, v12 op_sel:[0,1,0] op_sel_hi:[0,1,0]
	v_fma_mix_f32 v12, v8, v37, v12 op_sel_hi:[0,1,0]
	v_fma_mix_f32 v12, v9, v37, v12 op_sel:[0,1,0] op_sel_hi:[0,1,0]
	ds_read_b128 v[110:113], v10 offset:19712
	ds_read_b128 v[106:109], v10 offset:19456
	ds_read_b128 v[118:121], v10 offset:20224
	ds_read_b128 v[114:117], v10 offset:19968
	ds_read_b128 v[70:73], v11 offset:1280
	v_fma_mix_f32 v122, v6, v22, v180 op_sel_hi:[0,1,0]
	v_fma_mix_f32 v122, v7, v22, v122 op_sel:[0,1,0] op_sel_hi:[0,1,0]
	v_add_f32_dpp v12, v12, v12 row_ror:1 row_mask:0xf bank_mask:0xf bound_ctrl:1
	v_fma_mix_f32 v122, v8, v23, v122 op_sel_hi:[0,1,0]
	v_fma_mix_f32 v122, v9, v23, v122 op_sel:[0,1,0] op_sel_hi:[0,1,0]
	v_add_f32_dpp v12, v12, v12 row_ror:2 row_mask:0xf bank_mask:0xf bound_ctrl:1
	v_pk_fma_f32 v[48:49], v[44:45], v[66:67], v[6:7] op_sel:[0,1,0]
	v_pk_fma_f32 v[50:51], v[46:47], v[66:67], v[8:9] op_sel:[0,1,0]
	v_add_f32_dpp v12, v12, v12 row_ror:4 row_mask:0xf bank_mask:0xf bound_ctrl:1
	v_add_f32_dpp v83, v83, v83 row_ror:8 row_mask:0xf bank_mask:0xc
	v_add_f32_dpp v83, v52, v52 row_ror:8 row_mask:0xf bank_mask:0x3
	v_add_f32_dpp v100, v100, v100 row_ror:8 row_mask:0xf bank_mask:0xc
	v_add_f32_dpp v12, v12, v12 row_ror:8 row_mask:0xf bank_mask:0xf bound_ctrl:1
	v_pk_fma_f32 v[6:7], v[40:41], v[12:13], v[48:49] op_sel_hi:[1,0,1] neg_lo:[1,0,0] neg_hi:[1,0,0]
	v_pk_fma_f32 v[8:9], v[42:43], v[12:13], v[50:51] op_sel_hi:[1,0,1] neg_lo:[1,0,0] neg_hi:[1,0,0]
	s_waitcnt lgkmcnt(1)
	s_nop 0
	v_fma_mix_f32 v12, v6, v88, v180 op_sel_hi:[0,1,0]
	v_fma_mix_f32 v12, v7, v88, v12 op_sel:[0,1,0] op_sel_hi:[0,1,0]
	v_fma_mix_f32 v12, v8, v89, v12 op_sel_hi:[0,1,0]
	v_fma_mix_f32 v12, v9, v89, v12 op_sel:[0,1,0] op_sel_hi:[0,1,0]
	ds_read_b128 v[20:23], v10 offset:20736
	ds_read_b128 v[28:31], v10 offset:21248
	ds_read_b128 v[24:27], v10 offset:20992
	v_fma_mix_f32 v123, v6, v38, v180 op_sel_hi:[0,1,0]
	v_fma_mix_f32 v123, v7, v38, v123 op_sel:[0,1,0] op_sel_hi:[0,1,0]
	v_add_f32_dpp v12, v12, v12 row_ror:1 row_mask:0xf bank_mask:0xf bound_ctrl:1
	v_fma_mix_f32 v123, v8, v39, v123 op_sel_hi:[0,1,0]
	v_fma_mix_f32 v123, v9, v39, v123 op_sel:[0,1,0] op_sel_hi:[0,1,0]
	v_add_f32_dpp v12, v12, v12 row_ror:2 row_mask:0xf bank_mask:0xf bound_ctrl:1
	v_pk_fma_f32 v[48:49], v[96:97], v[68:69], v[6:7] op_sel_hi:[1,0,1]
	v_pk_fma_f32 v[50:51], v[98:99], v[68:69], v[8:9] op_sel_hi:[1,0,1]
	v_add_f32_dpp v12, v12, v12 row_ror:4 row_mask:0xf bank_mask:0xf bound_ctrl:1
	v_add_f32_dpp v100, v53, v53 row_ror:8 row_mask:0xf bank_mask:0x3
	v_add_f32_dpp v101, v101, v101 row_ror:8 row_mask:0xf bank_mask:0xc
	v_add_f32_dpp v101, v54, v54 row_ror:8 row_mask:0xf bank_mask:0x3
	v_add_f32_dpp v12, v12, v12 row_ror:8 row_mask:0xf bank_mask:0xf bound_ctrl:1
	v_pk_fma_f32 v[6:7], v[92:93], v[12:13], v[48:49] op_sel_hi:[1,0,1] neg_lo:[1,0,0] neg_hi:[1,0,0]
	v_pk_fma_f32 v[8:9], v[94:95], v[12:13], v[50:51] op_sel_hi:[1,0,1] neg_lo:[1,0,0] neg_hi:[1,0,0]
	v_fma_mix_f32 v12, v6, v110, v180 op_sel_hi:[0,1,0]
	v_fma_mix_f32 v12, v7, v110, v12 op_sel:[0,1,0] op_sel_hi:[0,1,0]
	v_fma_mix_f32 v12, v8, v111, v12 op_sel_hi:[0,1,0]
	v_fma_mix_f32 v12, v9, v111, v12 op_sel:[0,1,0] op_sel_hi:[0,1,0]
	ds_read_b128 v[36:39], v10 offset:21760
	ds_read_b128 v[44:47], v10 offset:22272
	ds_read_b128 v[40:43], v10 offset:22016
	v_fma_mix_f32 v124, v6, v90, v180 op_sel_hi:[0,1,0]
	v_fma_mix_f32 v124, v7, v90, v124 op_sel:[0,1,0] op_sel_hi:[0,1,0]
	v_add_f32_dpp v12, v12, v12 row_ror:1 row_mask:0xf bank_mask:0xf bound_ctrl:1
	v_fma_mix_f32 v124, v8, v91, v124 op_sel_hi:[0,1,0]
	v_fma_mix_f32 v124, v9, v91, v124 op_sel:[0,1,0] op_sel_hi:[0,1,0]
	v_add_f32_dpp v12, v12, v12 row_ror:2 row_mask:0xf bank_mask:0xf bound_ctrl:1
	v_pk_fma_f32 v[48:49], v[118:119], v[68:69], v[6:7] op_sel:[0,1,0]
	v_pk_fma_f32 v[50:51], v[120:121], v[68:69], v[8:9] op_sel:[0,1,0]
	v_add_f32_dpp v12, v12, v12 row_ror:4 row_mask:0xf bank_mask:0xf bound_ctrl:1
	v_add_f32_dpp v102, v102, v102 row_ror:8 row_mask:0xf bank_mask:0xc
	v_add_f32_dpp v102, v55, v55 row_ror:8 row_mask:0xf bank_mask:0x3
	v_add_f32_dpp v103, v103, v103 row_ror:8 row_mask:0xf bank_mask:0xc
	v_add_f32_dpp v12, v12, v12 row_ror:8 row_mask:0xf bank_mask:0xf bound_ctrl:1
	v_pk_fma_f32 v[6:7], v[114:115], v[12:13], v[48:49] op_sel_hi:[1,0,1] neg_lo:[1,0,0] neg_hi:[1,0,0]
	v_pk_fma_f32 v[8:9], v[116:117], v[12:13], v[50:51] op_sel_hi:[1,0,1] neg_lo:[1,0,0] neg_hi:[1,0,0]
	v_pk_mul_f32 v[6:7], v[6:7], v[106:107]
	v_pk_mul_f32 v[8:9], v[8:9], v[108:109]
	s_waitcnt lgkmcnt(0)
	s_nop 0
	v_fma_mix_f32 v12, v6, v20, v180 op_sel_hi:[0,1,0]
	v_fma_mix_f32 v12, v7, v20, v12 op_sel:[0,1,0] op_sel_hi:[0,1,0]
	v_fma_mix_f32 v12, v8, v21, v12 op_sel_hi:[0,1,0]
	v_fma_mix_f32 v12, v9, v21, v12 op_sel:[0,1,0] op_sel_hi:[0,1,0]
	ds_read_b128 v[88:91], v10 offset:22784
	ds_read_b128 v[96:99], v10 offset:23296
	ds_read_b128 v[92:95], v10 offset:23040
	v_fma_mix_f32 v125, v6, v112, v180 op_sel_hi:[0,1,0]
	v_fma_mix_f32 v125, v7, v112, v125 op_sel:[0,1,0] op_sel_hi:[0,1,0]
	v_add_f32_dpp v12, v12, v12 row_ror:1 row_mask:0xf bank_mask:0xf bound_ctrl:1
	v_fma_mix_f32 v125, v8, v113, v125 op_sel_hi:[0,1,0]
	v_fma_mix_f32 v125, v9, v113, v125 op_sel:[0,1,0] op_sel_hi:[0,1,0]
	v_add_f32_dpp v12, v12, v12 row_ror:2 row_mask:0xf bank_mask:0xf bound_ctrl:1
	v_pk_fma_f32 v[48:49], v[28:29], v[70:71], v[6:7] op_sel_hi:[1,0,1]
	v_pk_fma_f32 v[50:51], v[30:31], v[70:71], v[8:9] op_sel_hi:[1,0,1]
	v_add_f32_dpp v12, v12, v12 row_ror:4 row_mask:0xf bank_mask:0xf bound_ctrl:1
	v_add_f32_dpp v103, v56, v56 row_ror:8 row_mask:0xf bank_mask:0x3
	v_add_f32_dpp v104, v104, v104 row_ror:8 row_mask:0xf bank_mask:0xc
	v_add_f32_dpp v104, v57, v57 row_ror:8 row_mask:0xf bank_mask:0x3
	v_add_f32_dpp v12, v12, v12 row_ror:8 row_mask:0xf bank_mask:0xf bound_ctrl:1
	v_pk_fma_f32 v[6:7], v[24:25], v[12:13], v[48:49] op_sel_hi:[1,0,1] neg_lo:[1,0,0] neg_hi:[1,0,0]
	v_pk_fma_f32 v[8:9], v[26:27], v[12:13], v[50:51] op_sel_hi:[1,0,1] neg_lo:[1,0,0] neg_hi:[1,0,0]
	v_fma_mix_f32 v12, v6, v36, v180 op_sel_hi:[0,1,0]
	v_fma_mix_f32 v12, v7, v36, v12 op_sel:[0,1,0] op_sel_hi:[0,1,0]
	v_fma_mix_f32 v12, v8, v37, v12 op_sel_hi:[0,1,0]
	v_fma_mix_f32 v12, v9, v37, v12 op_sel:[0,1,0] op_sel_hi:[0,1,0]
	ds_read_b128 v[110:113], v10 offset:23808
	ds_read_b128 v[106:109], v10 offset:23552
	ds_read_b128 v[118:121], v10 offset:24320
	ds_read_b128 v[114:117], v10 offset:24064
	ds_read_b128 v[66:69], v11 offset:1536
	v_fma_mix_f32 v126, v6, v22, v180 op_sel_hi:[0,1,0]
	v_fma_mix_f32 v126, v7, v22, v126 op_sel:[0,1,0] op_sel_hi:[0,1,0]
	v_add_f32_dpp v12, v12, v12 row_ror:1 row_mask:0xf bank_mask:0xf bound_ctrl:1
	v_fma_mix_f32 v126, v8, v23, v126 op_sel_hi:[0,1,0]
	v_fma_mix_f32 v126, v9, v23, v126 op_sel:[0,1,0] op_sel_hi:[0,1,0]
	v_add_f32_dpp v12, v12, v12 row_ror:2 row_mask:0xf bank_mask:0xf bound_ctrl:1
	v_pk_fma_f32 v[48:49], v[44:45], v[70:71], v[6:7] op_sel:[0,1,0]
	v_pk_fma_f32 v[50:51], v[46:47], v[70:71], v[8:9] op_sel:[0,1,0]
	v_add_f32_dpp v12, v12, v12 row_ror:4 row_mask:0xf bank_mask:0xf bound_ctrl:1
	v_add_f32_dpp v105, v105, v105 row_ror:8 row_mask:0xf bank_mask:0xc
	v_add_f32_dpp v105, v81, v81 row_ror:8 row_mask:0xf bank_mask:0x3
	v_add_f32_dpp v12, v12, v12 row_ror:8 row_mask:0xf bank_mask:0xf bound_ctrl:1
	v_pk_fma_f32 v[6:7], v[40:41], v[12:13], v[48:49] op_sel_hi:[1,0,1] neg_lo:[1,0,0] neg_hi:[1,0,0]
	v_pk_fma_f32 v[8:9], v[42:43], v[12:13], v[50:51] op_sel_hi:[1,0,1] neg_lo:[1,0,0] neg_hi:[1,0,0]
	s_waitcnt lgkmcnt(1)
	s_nop 0
	v_fma_mix_f32 v12, v6, v88, v180 op_sel_hi:[0,1,0]
	v_fma_mix_f32 v12, v7, v88, v12 op_sel:[0,1,0] op_sel_hi:[0,1,0]
	v_fma_mix_f32 v12, v8, v89, v12 op_sel_hi:[0,1,0]
	v_fma_mix_f32 v12, v9, v89, v12 op_sel:[0,1,0] op_sel_hi:[0,1,0]
	ds_read_b128 v[20:23], v10 offset:24832
	ds_read_b128 v[28:31], v10 offset:25344
	ds_read_b128 v[24:27], v10 offset:25088
	v_fma_mix_f32 v127, v6, v38, v180 op_sel_hi:[0,1,0]
	v_fma_mix_f32 v127, v7, v38, v127 op_sel:[0,1,0] op_sel_hi:[0,1,0]
	v_add_f32_dpp v12, v12, v12 row_ror:1 row_mask:0xf bank_mask:0xf bound_ctrl:1
	v_fma_mix_f32 v127, v8, v39, v127 op_sel_hi:[0,1,0]
	v_fma_mix_f32 v127, v9, v39, v127 op_sel:[0,1,0] op_sel_hi:[0,1,0]
	v_add_f32_dpp v12, v12, v12 row_ror:2 row_mask:0xf bank_mask:0xf bound_ctrl:1
	v_pk_fma_f32 v[48:49], v[96:97], v[72:73], v[6:7] op_sel_hi:[1,0,1]
	v_pk_fma_f32 v[50:51], v[98:99], v[72:73], v[8:9] op_sel_hi:[1,0,1]
	v_add_f32_dpp v12, v12, v12 row_ror:4 row_mask:0xf bank_mask:0xf bound_ctrl:1
	v_add_f32_dpp v61, v61, v61 row_ror:8 row_mask:0xf bank_mask:0xc
	v_add_f32_dpp v61, v82, v82 row_ror:8 row_mask:0xf bank_mask:0x3
	v_add_f32_dpp v12, v12, v12 row_ror:8 row_mask:0xf bank_mask:0xf bound_ctrl:1
	v_pk_fma_f32 v[6:7], v[92:93], v[12:13], v[48:49] op_sel_hi:[1,0,1] neg_lo:[1,0,0] neg_hi:[1,0,0]
	v_pk_fma_f32 v[8:9], v[94:95], v[12:13], v[50:51] op_sel_hi:[1,0,1] neg_lo:[1,0,0] neg_hi:[1,0,0]
	v_fma_mix_f32 v12, v6, v110, v180 op_sel_hi:[0,1,0]
	v_fma_mix_f32 v12, v7, v110, v12 op_sel:[0,1,0] op_sel_hi:[0,1,0]
	v_fma_mix_f32 v12, v8, v111, v12 op_sel_hi:[0,1,0]
	v_fma_mix_f32 v12, v9, v111, v12 op_sel:[0,1,0] op_sel_hi:[0,1,0]
	ds_read_b128 v[36:39], v10 offset:25856
	ds_read_b128 v[44:47], v10 offset:26368
	ds_read_b128 v[40:43], v10 offset:26112
	v_fma_mix_f32 v128, v6, v90, v180 op_sel_hi:[0,1,0]
	v_fma_mix_f32 v128, v7, v90, v128 op_sel:[0,1,0] op_sel_hi:[0,1,0]
	v_add_f32_dpp v12, v12, v12 row_ror:1 row_mask:0xf bank_mask:0xf bound_ctrl:1
	v_fma_mix_f32 v128, v8, v91, v128 op_sel_hi:[0,1,0]
	v_fma_mix_f32 v128, v9, v91, v128 op_sel:[0,1,0] op_sel_hi:[0,1,0]
	v_add_f32_dpp v12, v12, v12 row_ror:2 row_mask:0xf bank_mask:0xf bound_ctrl:1
	v_pk_fma_f32 v[48:49], v[118:119], v[72:73], v[6:7] op_sel:[0,1,0]
	v_pk_fma_f32 v[50:51], v[120:121], v[72:73], v[8:9] op_sel:[0,1,0]
	v_add_f32_dpp v12, v12, v12 row_ror:4 row_mask:0xf bank_mask:0xf bound_ctrl:1
	v_add_f32_dpp v103, v103, v103 row_ror:4 row_mask:0xf bank_mask:0xa
	v_add_f32_dpp v103, v83, v83 row_ror:12 row_mask:0xf bank_mask:0x5
	v_add_f32_dpp v104, v104, v104 row_ror:4 row_mask:0xf bank_mask:0xa
	v_add_f32_dpp v12, v12, v12 row_ror:8 row_mask:0xf bank_mask:0xf bound_ctrl:1
	v_pk_fma_f32 v[6:7], v[114:115], v[12:13], v[48:49] op_sel_hi:[1,0,1] neg_lo:[1,0,0] neg_hi:[1,0,0]
	v_pk_fma_f32 v[8:9], v[116:117], v[12:13], v[50:51] op_sel_hi:[1,0,1] neg_lo:[1,0,0] neg_hi:[1,0,0]
	v_pk_mul_f32 v[6:7], v[6:7], v[106:107]
	v_pk_mul_f32 v[8:9], v[8:9], v[108:109]
	s_waitcnt lgkmcnt(0)
	s_nop 0
	v_fma_mix_f32 v12, v6, v20, v180 op_sel_hi:[0,1,0]
	v_fma_mix_f32 v12, v7, v20, v12 op_sel:[0,1,0] op_sel_hi:[0,1,0]
	v_fma_mix_f32 v12, v8, v21, v12 op_sel_hi:[0,1,0]
	v_fma_mix_f32 v12, v9, v21, v12 op_sel:[0,1,0] op_sel_hi:[0,1,0]
	ds_read_b128 v[88:91], v10 offset:26880
	ds_read_b128 v[96:99], v10 offset:27392
	ds_read_b128 v[92:95], v10 offset:27136
	v_fma_mix_f32 v129, v6, v112, v180 op_sel_hi:[0,1,0]
	v_fma_mix_f32 v129, v7, v112, v129 op_sel:[0,1,0] op_sel_hi:[0,1,0]
	v_add_f32_dpp v12, v12, v12 row_ror:1 row_mask:0xf bank_mask:0xf bound_ctrl:1
	v_fma_mix_f32 v129, v8, v113, v129 op_sel_hi:[0,1,0]
	v_fma_mix_f32 v129, v9, v113, v129 op_sel:[0,1,0] op_sel_hi:[0,1,0]
	v_add_f32_dpp v12, v12, v12 row_ror:2 row_mask:0xf bank_mask:0xf bound_ctrl:1
	v_pk_fma_f32 v[48:49], v[28:29], v[66:67], v[6:7] op_sel_hi:[1,0,1]
	v_pk_fma_f32 v[50:51], v[30:31], v[66:67], v[8:9] op_sel_hi:[1,0,1]
	v_add_f32_dpp v12, v12, v12 row_ror:4 row_mask:0xf bank_mask:0xf bound_ctrl:1
	v_add_f32_dpp v104, v100, v100 row_ror:12 row_mask:0xf bank_mask:0x5
	v_add_f32_dpp v105, v105, v105 row_ror:4 row_mask:0xf bank_mask:0xa
	v_add_f32_dpp v105, v101, v101 row_ror:12 row_mask:0xf bank_mask:0x5
	v_add_f32_dpp v12, v12, v12 row_ror:8 row_mask:0xf bank_mask:0xf bound_ctrl:1
	v_pk_fma_f32 v[6:7], v[24:25], v[12:13], v[48:49] op_sel_hi:[1,0,1] neg_lo:[1,0,0] neg_hi:[1,0,0]
	v_pk_fma_f32 v[8:9], v[26:27], v[12:13], v[50:51] op_sel_hi:[1,0,1] neg_lo:[1,0,0] neg_hi:[1,0,0]
	v_fma_mix_f32 v12, v6, v36, v180 op_sel_hi:[0,1,0]
	v_fma_mix_f32 v12, v7, v36, v12 op_sel:[0,1,0] op_sel_hi:[0,1,0]
	v_fma_mix_f32 v12, v8, v37, v12 op_sel_hi:[0,1,0]
	v_fma_mix_f32 v12, v9, v37, v12 op_sel:[0,1,0] op_sel_hi:[0,1,0]
	ds_read_b128 v[110:113], v10 offset:27904
	ds_read_b128 v[106:109], v10 offset:27648
	ds_read_b128 v[118:121], v10 offset:28416
	ds_read_b128 v[114:117], v10 offset:28160
	ds_read_b128 v[70:73], v11 offset:1792
	v_fma_mix_f32 v130, v6, v22, v180 op_sel_hi:[0,1,0]
	v_fma_mix_f32 v130, v7, v22, v130 op_sel:[0,1,0] op_sel_hi:[0,1,0]
	v_add_f32_dpp v12, v12, v12 row_ror:1 row_mask:0xf bank_mask:0xf bound_ctrl:1
	v_fma_mix_f32 v130, v8, v23, v130 op_sel_hi:[0,1,0]
	v_fma_mix_f32 v130, v9, v23, v130 op_sel:[0,1,0] op_sel_hi:[0,1,0]
	v_add_f32_dpp v12, v12, v12 row_ror:2 row_mask:0xf bank_mask:0xf bound_ctrl:1
	v_pk_fma_f32 v[48:49], v[44:45], v[66:67], v[6:7] op_sel:[0,1,0]
	v_pk_fma_f32 v[50:51], v[46:47], v[66:67], v[8:9] op_sel:[0,1,0]
	v_add_f32_dpp v12, v12, v12 row_ror:4 row_mask:0xf bank_mask:0xf bound_ctrl:1
	v_add_f32_dpp v61, v61, v61 row_ror:4 row_mask:0xf bank_mask:0xa
	v_add_f32_dpp v61, v102, v102 row_ror:12 row_mask:0xf bank_mask:0x5
	v_add_f32_dpp v12, v12, v12 row_ror:8 row_mask:0xf bank_mask:0xf bound_ctrl:1
	v_pk_fma_f32 v[6:7], v[40:41], v[12:13], v[48:49] op_sel_hi:[1,0,1] neg_lo:[1,0,0] neg_hi:[1,0,0]
	v_pk_fma_f32 v[8:9], v[42:43], v[12:13], v[50:51] op_sel_hi:[1,0,1] neg_lo:[1,0,0] neg_hi:[1,0,0]
	s_waitcnt lgkmcnt(1)
	s_nop 0
	v_fma_mix_f32 v12, v6, v88, v180 op_sel_hi:[0,1,0]
	v_fma_mix_f32 v12, v7, v88, v12 op_sel:[0,1,0] op_sel_hi:[0,1,0]
	v_fma_mix_f32 v12, v8, v89, v12 op_sel_hi:[0,1,0]
	v_fma_mix_f32 v12, v9, v89, v12 op_sel:[0,1,0] op_sel_hi:[0,1,0]
	ds_read_b128 v[20:23], v10 offset:28928
	ds_read_b128 v[28:31], v10 offset:29440
	ds_read_b128 v[24:27], v10 offset:29184
	v_fma_mix_f32 v131, v6, v38, v180 op_sel_hi:[0,1,0]
	v_fma_mix_f32 v131, v7, v38, v131 op_sel:[0,1,0] op_sel_hi:[0,1,0]
	v_add_f32_dpp v12, v12, v12 row_ror:1 row_mask:0xf bank_mask:0xf bound_ctrl:1
	v_fma_mix_f32 v131, v8, v39, v131 op_sel_hi:[0,1,0]
	v_fma_mix_f32 v131, v9, v39, v131 op_sel:[0,1,0] op_sel_hi:[0,1,0]
	v_add_f32_dpp v12, v12, v12 row_ror:2 row_mask:0xf bank_mask:0xf bound_ctrl:1
	v_pk_fma_f32 v[48:49], v[96:97], v[68:69], v[6:7] op_sel_hi:[1,0,1]
	v_pk_fma_f32 v[50:51], v[98:99], v[68:69], v[8:9] op_sel_hi:[1,0,1]
	v_add_f32_dpp v12, v12, v12 row_ror:4 row_mask:0xf bank_mask:0xf bound_ctrl:1
	v_cndmask_b32_e64 v62, v105, v103, s[38:39]
	v_cndmask_b32_e64 v63, v103, v105, s[38:39]
	v_add_f32_dpp v12, v12, v12 row_ror:8 row_mask:0xf bank_mask:0xf bound_ctrl:1
	v_pk_fma_f32 v[6:7], v[92:93], v[12:13], v[48:49] op_sel_hi:[1,0,1] neg_lo:[1,0,0] neg_hi:[1,0,0]
	v_pk_fma_f32 v[8:9], v[94:95], v[12:13], v[50:51] op_sel_hi:[1,0,1] neg_lo:[1,0,0] neg_hi:[1,0,0]
	v_fma_mix_f32 v12, v6, v110, v180 op_sel_hi:[0,1,0]
	v_fma_mix_f32 v12, v7, v110, v12 op_sel:[0,1,0] op_sel_hi:[0,1,0]
	v_fma_mix_f32 v12, v8, v111, v12 op_sel_hi:[0,1,0]
	v_fma_mix_f32 v12, v9, v111, v12 op_sel:[0,1,0] op_sel_hi:[0,1,0]
	ds_read_b128 v[36:39], v10 offset:29952
	ds_read_b128 v[44:47], v10 offset:30464
	ds_read_b128 v[40:43], v10 offset:30208
	v_fma_mix_f32 v132, v6, v90, v180 op_sel_hi:[0,1,0]
	v_fma_mix_f32 v132, v7, v90, v132 op_sel:[0,1,0] op_sel_hi:[0,1,0]
	v_add_f32_dpp v12, v12, v12 row_ror:1 row_mask:0xf bank_mask:0xf bound_ctrl:1
	v_fma_mix_f32 v132, v8, v91, v132 op_sel_hi:[0,1,0]
	v_fma_mix_f32 v132, v9, v91, v132 op_sel:[0,1,0] op_sel_hi:[0,1,0]
	v_add_f32_dpp v12, v12, v12 row_ror:2 row_mask:0xf bank_mask:0xf bound_ctrl:1
	v_pk_fma_f32 v[48:49], v[118:119], v[68:69], v[6:7] op_sel:[0,1,0]
	v_pk_fma_f32 v[50:51], v[120:121], v[68:69], v[8:9] op_sel:[0,1,0]
	v_add_f32_dpp v12, v12, v12 row_ror:4 row_mask:0xf bank_mask:0xf bound_ctrl:1
	v_cndmask_b32_e64 v64, v61, v104, s[38:39]
	v_cndmask_b32_e64 v65, v104, v61, s[38:39]
	v_add_f32_dpp v12, v12, v12 row_ror:8 row_mask:0xf bank_mask:0xf bound_ctrl:1
	v_pk_fma_f32 v[6:7], v[114:115], v[12:13], v[48:49] op_sel_hi:[1,0,1] neg_lo:[1,0,0] neg_hi:[1,0,0]
	v_pk_fma_f32 v[8:9], v[116:117], v[12:13], v[50:51] op_sel_hi:[1,0,1] neg_lo:[1,0,0] neg_hi:[1,0,0]
	v_pk_mul_f32 v[6:7], v[6:7], v[106:107]
	v_pk_mul_f32 v[8:9], v[8:9], v[108:109]
	s_waitcnt lgkmcnt(0)
	s_nop 0
	v_fma_mix_f32 v12, v6, v20, v180 op_sel_hi:[0,1,0]
	v_fma_mix_f32 v12, v7, v20, v12 op_sel:[0,1,0] op_sel_hi:[0,1,0]
	v_fma_mix_f32 v12, v8, v21, v12 op_sel_hi:[0,1,0]
	v_fma_mix_f32 v12, v9, v21, v12 op_sel:[0,1,0] op_sel_hi:[0,1,0]
	ds_read_b128 v[88:91], v10 offset:30976
	ds_read_b128 v[96:99], v10 offset:31488
	ds_read_b128 v[92:95], v10 offset:31232
	v_fma_mix_f32 v133, v6, v112, v180 op_sel_hi:[0,1,0]
	v_fma_mix_f32 v133, v7, v112, v133 op_sel:[0,1,0] op_sel_hi:[0,1,0]
	v_add_f32_dpp v12, v12, v12 row_ror:1 row_mask:0xf bank_mask:0xf bound_ctrl:1
	v_fma_mix_f32 v133, v8, v113, v133 op_sel_hi:[0,1,0]
	v_fma_mix_f32 v133, v9, v113, v133 op_sel:[0,1,0] op_sel_hi:[0,1,0]
	v_add_f32_dpp v12, v12, v12 row_ror:2 row_mask:0xf bank_mask:0xf bound_ctrl:1
	v_pk_fma_f32 v[48:49], v[28:29], v[70:71], v[6:7] op_sel_hi:[1,0,1]
	v_pk_fma_f32 v[50:51], v[30:31], v[70:71], v[8:9] op_sel_hi:[1,0,1]
	v_add_f32_dpp v12, v12, v12 row_ror:4 row_mask:0xf bank_mask:0xf bound_ctrl:1
	v_add_f32_dpp v62, v63, v62 quad_perm:[2,3,0,1] row_mask:0xf bank_mask:0xf bound_ctrl:1
	v_add_f32_dpp v63, v65, v64 quad_perm:[2,3,0,1] row_mask:0xf bank_mask:0xf bound_ctrl:1
	v_add_f32_dpp v12, v12, v12 row_ror:8 row_mask:0xf bank_mask:0xf bound_ctrl:1
	v_pk_fma_f32 v[6:7], v[24:25], v[12:13], v[48:49] op_sel_hi:[1,0,1] neg_lo:[1,0,0] neg_hi:[1,0,0]
	v_pk_fma_f32 v[8:9], v[26:27], v[12:13], v[50:51] op_sel_hi:[1,0,1] neg_lo:[1,0,0] neg_hi:[1,0,0]
	v_fma_mix_f32 v12, v6, v36, v180 op_sel_hi:[0,1,0]
	v_fma_mix_f32 v12, v7, v36, v12 op_sel:[0,1,0] op_sel_hi:[0,1,0]
	v_fma_mix_f32 v12, v8, v37, v12 op_sel_hi:[0,1,0]
	v_fma_mix_f32 v12, v9, v37, v12 op_sel:[0,1,0] op_sel_hi:[0,1,0]
	ds_read_b128 v[110:113], v10 offset:32000
	ds_read_b128 v[106:109], v10 offset:31744
	ds_read_b128 v[118:121], v10 offset:32512
	ds_read_b128 v[114:117], v10 offset:32256
	ds_read_b128 v[66:69], v11 offset:2048
	v_fma_mix_f32 v134, v6, v22, v180 op_sel_hi:[0,1,0]
	v_fma_mix_f32 v134, v7, v22, v134 op_sel:[0,1,0] op_sel_hi:[0,1,0]
	v_add_f32_dpp v12, v12, v12 row_ror:1 row_mask:0xf bank_mask:0xf bound_ctrl:1
	v_fma_mix_f32 v134, v8, v23, v134 op_sel_hi:[0,1,0]
	v_fma_mix_f32 v134, v9, v23, v134 op_sel:[0,1,0] op_sel_hi:[0,1,0]
	v_add_f32_dpp v12, v12, v12 row_ror:2 row_mask:0xf bank_mask:0xf bound_ctrl:1
	v_pk_fma_f32 v[48:49], v[44:45], v[70:71], v[6:7] op_sel:[0,1,0]
	v_pk_fma_f32 v[50:51], v[46:47], v[70:71], v[8:9] op_sel:[0,1,0]
	v_add_f32_dpp v12, v12, v12 row_ror:4 row_mask:0xf bank_mask:0xf bound_ctrl:1
	v_cndmask_b32_e64 v65, v63, v62, s[40:41]
	v_cndmask_b32_e64 v62, v62, v63, s[40:41]
	v_add_f32_dpp v12, v12, v12 row_ror:8 row_mask:0xf bank_mask:0xf bound_ctrl:1
	v_pk_fma_f32 v[6:7], v[40:41], v[12:13], v[48:49] op_sel_hi:[1,0,1] neg_lo:[1,0,0] neg_hi:[1,0,0]
	v_pk_fma_f32 v[8:9], v[42:43], v[12:13], v[50:51] op_sel_hi:[1,0,1] neg_lo:[1,0,0] neg_hi:[1,0,0]
	s_waitcnt lgkmcnt(1)
	s_nop 0
	v_fma_mix_f32 v12, v6, v88, v180 op_sel_hi:[0,1,0]
	v_fma_mix_f32 v12, v7, v88, v12 op_sel:[0,1,0] op_sel_hi:[0,1,0]
	v_fma_mix_f32 v12, v8, v89, v12 op_sel_hi:[0,1,0]
	v_fma_mix_f32 v12, v9, v89, v12 op_sel:[0,1,0] op_sel_hi:[0,1,0]
	ds_read_b128 v[20:23], v10 offset:33024
	ds_read_b128 v[28:31], v10 offset:33536
	ds_read_b128 v[24:27], v10 offset:33280
	v_fma_mix_f32 v135, v6, v38, v180 op_sel_hi:[0,1,0]
	v_fma_mix_f32 v135, v7, v38, v135 op_sel:[0,1,0] op_sel_hi:[0,1,0]
	v_add_f32_dpp v12, v12, v12 row_ror:1 row_mask:0xf bank_mask:0xf bound_ctrl:1
	v_fma_mix_f32 v135, v8, v39, v135 op_sel_hi:[0,1,0]
	v_fma_mix_f32 v135, v9, v39, v135 op_sel:[0,1,0] op_sel_hi:[0,1,0]
	v_add_f32_dpp v12, v12, v12 row_ror:2 row_mask:0xf bank_mask:0xf bound_ctrl:1
	v_pk_fma_f32 v[48:49], v[96:97], v[72:73], v[6:7] op_sel_hi:[1,0,1]
	v_pk_fma_f32 v[50:51], v[98:99], v[72:73], v[8:9] op_sel_hi:[1,0,1]
	v_add_f32_dpp v12, v12, v12 row_ror:4 row_mask:0xf bank_mask:0xf bound_ctrl:1
	v_add_f32_dpp v62, v62, v65 quad_perm:[1,0,3,2] row_mask:0xf bank_mask:0xf bound_ctrl:1
	v_cvt_pk_bf16_f32 v62, v62, v62
	v_add_f32_dpp v12, v12, v12 row_ror:8 row_mask:0xf bank_mask:0xf bound_ctrl:1
	v_pk_fma_f32 v[6:7], v[92:93], v[12:13], v[48:49] op_sel_hi:[1,0,1] neg_lo:[1,0,0] neg_hi:[1,0,0]
	v_pk_fma_f32 v[8:9], v[94:95], v[12:13], v[50:51] op_sel_hi:[1,0,1] neg_lo:[1,0,0] neg_hi:[1,0,0]
	v_fma_mix_f32 v12, v6, v110, v180 op_sel_hi:[0,1,0]
	v_fma_mix_f32 v12, v7, v110, v12 op_sel:[0,1,0] op_sel_hi:[0,1,0]
	v_fma_mix_f32 v12, v8, v111, v12 op_sel_hi:[0,1,0]
	v_fma_mix_f32 v12, v9, v111, v12 op_sel:[0,1,0] op_sel_hi:[0,1,0]
	ds_read_b128 v[36:39], v10 offset:34048
	ds_read_b128 v[44:47], v10 offset:34560
	ds_read_b128 v[40:43], v10 offset:34304
	v_fma_mix_f32 v136, v6, v90, v180 op_sel_hi:[0,1,0]
	v_fma_mix_f32 v136, v7, v90, v136 op_sel:[0,1,0] op_sel_hi:[0,1,0]
	v_add_f32_dpp v12, v12, v12 row_ror:1 row_mask:0xf bank_mask:0xf bound_ctrl:1
	v_fma_mix_f32 v136, v8, v91, v136 op_sel_hi:[0,1,0]
	v_fma_mix_f32 v136, v9, v91, v136 op_sel:[0,1,0] op_sel_hi:[0,1,0]
	v_add_f32_dpp v12, v12, v12 row_ror:2 row_mask:0xf bank_mask:0xf bound_ctrl:1
	v_pk_fma_f32 v[48:49], v[118:119], v[72:73], v[6:7] op_sel:[0,1,0]
	v_pk_fma_f32 v[50:51], v[120:121], v[72:73], v[8:9] op_sel:[0,1,0]
	v_add_f32_dpp v12, v12, v12 row_ror:4 row_mask:0xf bank_mask:0xf bound_ctrl:1
	global_store_short v[2:3], v62, off
	v_lshl_add_u64 v[2:3], v[2:3], 0, s[84:85]
	v_add_f32_dpp v12, v12, v12 row_ror:8 row_mask:0xf bank_mask:0xf bound_ctrl:1
	v_pk_fma_f32 v[6:7], v[114:115], v[12:13], v[48:49] op_sel_hi:[1,0,1] neg_lo:[1,0,0] neg_hi:[1,0,0]
	v_pk_fma_f32 v[8:9], v[116:117], v[12:13], v[50:51] op_sel_hi:[1,0,1] neg_lo:[1,0,0] neg_hi:[1,0,0]
	v_pk_mul_f32 v[6:7], v[6:7], v[106:107]
	v_pk_mul_f32 v[8:9], v[8:9], v[108:109]
	s_waitcnt lgkmcnt(0)
	s_nop 0
	v_fma_mix_f32 v12, v6, v20, v180 op_sel_hi:[0,1,0]
	v_fma_mix_f32 v12, v7, v20, v12 op_sel:[0,1,0] op_sel_hi:[0,1,0]
	v_fma_mix_f32 v12, v8, v21, v12 op_sel_hi:[0,1,0]
	v_fma_mix_f32 v12, v9, v21, v12 op_sel:[0,1,0] op_sel_hi:[0,1,0]
	ds_read_b128 v[88:91], v10 offset:35072
	ds_read_b128 v[96:99], v10 offset:35584
	ds_read_b128 v[92:95], v10 offset:35328
	v_fma_mix_f32 v137, v6, v112, v180 op_sel_hi:[0,1,0]
	v_fma_mix_f32 v137, v7, v112, v137 op_sel:[0,1,0] op_sel_hi:[0,1,0]
	v_add_f32_dpp v12, v12, v12 row_ror:1 row_mask:0xf bank_mask:0xf bound_ctrl:1
	v_fma_mix_f32 v137, v8, v113, v137 op_sel_hi:[0,1,0]
	v_fma_mix_f32 v137, v9, v113, v137 op_sel:[0,1,0] op_sel_hi:[0,1,0]
	v_add_f32_dpp v12, v12, v12 row_ror:2 row_mask:0xf bank_mask:0xf bound_ctrl:1
	v_pk_fma_f32 v[48:49], v[28:29], v[66:67], v[6:7] op_sel_hi:[1,0,1]
	v_pk_fma_f32 v[50:51], v[30:31], v[66:67], v[8:9] op_sel_hi:[1,0,1]
	v_add_f32_dpp v12, v12, v12 row_ror:4 row_mask:0xf bank_mask:0xf bound_ctrl:1
	s_nop 1
	s_nop 0
	v_add_f32_dpp v12, v12, v12 row_ror:8 row_mask:0xf bank_mask:0xf bound_ctrl:1
	v_pk_fma_f32 v[6:7], v[24:25], v[12:13], v[48:49] op_sel_hi:[1,0,1] neg_lo:[1,0,0] neg_hi:[1,0,0]
	v_pk_fma_f32 v[8:9], v[26:27], v[12:13], v[50:51] op_sel_hi:[1,0,1] neg_lo:[1,0,0] neg_hi:[1,0,0]
	v_fma_mix_f32 v12, v6, v36, v180 op_sel_hi:[0,1,0]
	v_fma_mix_f32 v12, v7, v36, v12 op_sel:[0,1,0] op_sel_hi:[0,1,0]
	v_fma_mix_f32 v12, v8, v37, v12 op_sel_hi:[0,1,0]
	v_fma_mix_f32 v12, v9, v37, v12 op_sel:[0,1,0] op_sel_hi:[0,1,0]
	ds_read_b128 v[110:113], v10 offset:36096
	ds_read_b128 v[106:109], v10 offset:35840
	ds_read_b128 v[118:121], v10 offset:36608
	ds_read_b128 v[114:117], v10 offset:36352
	ds_read_b128 v[70:73], v11 offset:2304
	v_fma_mix_f32 v52, v6, v22, v180 op_sel_hi:[0,1,0]
	v_fma_mix_f32 v52, v7, v22, v52 op_sel:[0,1,0] op_sel_hi:[0,1,0]
	v_add_f32_dpp v12, v12, v12 row_ror:1 row_mask:0xf bank_mask:0xf bound_ctrl:1
	v_fma_mix_f32 v52, v8, v23, v52 op_sel_hi:[0,1,0]
	v_fma_mix_f32 v52, v9, v23, v52 op_sel:[0,1,0] op_sel_hi:[0,1,0]
	v_add_f32_dpp v12, v12, v12 row_ror:2 row_mask:0xf bank_mask:0xf bound_ctrl:1
	v_pk_fma_f32 v[48:49], v[44:45], v[66:67], v[6:7] op_sel:[0,1,0]
	v_pk_fma_f32 v[50:51], v[46:47], v[66:67], v[8:9] op_sel:[0,1,0]
	v_add_f32_dpp v12, v12, v12 row_ror:4 row_mask:0xf bank_mask:0xf bound_ctrl:1
	v_add_f32_dpp v130, v130, v130 row_ror:8 row_mask:0xf bank_mask:0xc
	v_add_f32_dpp v130, v122, v122 row_ror:8 row_mask:0xf bank_mask:0x3
	v_add_f32_dpp v131, v131, v131 row_ror:8 row_mask:0xf bank_mask:0xc
	v_add_f32_dpp v12, v12, v12 row_ror:8 row_mask:0xf bank_mask:0xf bound_ctrl:1
	v_pk_fma_f32 v[6:7], v[40:41], v[12:13], v[48:49] op_sel_hi:[1,0,1] neg_lo:[1,0,0] neg_hi:[1,0,0]
	v_pk_fma_f32 v[8:9], v[42:43], v[12:13], v[50:51] op_sel_hi:[1,0,1] neg_lo:[1,0,0] neg_hi:[1,0,0]
	s_waitcnt lgkmcnt(1)
	s_nop 0
	v_fma_mix_f32 v12, v6, v88, v180 op_sel_hi:[0,1,0]
	v_fma_mix_f32 v12, v7, v88, v12 op_sel:[0,1,0] op_sel_hi:[0,1,0]
	v_fma_mix_f32 v12, v8, v89, v12 op_sel_hi:[0,1,0]
	v_fma_mix_f32 v12, v9, v89, v12 op_sel:[0,1,0] op_sel_hi:[0,1,0]
	ds_read_b128 v[20:23], v10 offset:37120
	ds_read_b128 v[28:31], v10 offset:37632
	ds_read_b128 v[24:27], v10 offset:37376
	v_fma_mix_f32 v53, v6, v38, v180 op_sel_hi:[0,1,0]
	v_fma_mix_f32 v53, v7, v38, v53 op_sel:[0,1,0] op_sel_hi:[0,1,0]
	v_add_f32_dpp v12, v12, v12 row_ror:1 row_mask:0xf bank_mask:0xf bound_ctrl:1
	v_fma_mix_f32 v53, v8, v39, v53 op_sel_hi:[0,1,0]
	v_fma_mix_f32 v53, v9, v39, v53 op_sel:[0,1,0] op_sel_hi:[0,1,0]
	v_add_f32_dpp v12, v12, v12 row_ror:2 row_mask:0xf bank_mask:0xf bound_ctrl:1
	v_pk_fma_f32 v[48:49], v[96:97], v[68:69], v[6:7] op_sel_hi:[1,0,1]
	v_pk_fma_f32 v[50:51], v[98:99], v[68:69], v[8:9] op_sel_hi:[1,0,1]
	v_add_f32_dpp v12, v12, v12 row_ror:4 row_mask:0xf bank_mask:0xf bound_ctrl:1
	v_add_f32_dpp v131, v123, v123 row_ror:8 row_mask:0xf bank_mask:0x3
	v_add_f32_dpp v132, v132, v132 row_ror:8 row_mask:0xf bank_mask:0xc
	v_add_f32_dpp v132, v124, v124 row_ror:8 row_mask:0xf bank_mask:0x3
	v_add_f32_dpp v12, v12, v12 row_ror:8 row_mask:0xf bank_mask:0xf bound_ctrl:1
	v_pk_fma_f32 v[6:7], v[92:93], v[12:13], v[48:49] op_sel_hi:[1,0,1] neg_lo:[1,0,0] neg_hi:[1,0,0]
	v_pk_fma_f32 v[8:9], v[94:95], v[12:13], v[50:51] op_sel_hi:[1,0,1] neg_lo:[1,0,0] neg_hi:[1,0,0]
	v_fma_mix_f32 v12, v6, v110, v180 op_sel_hi:[0,1,0]
	v_fma_mix_f32 v12, v7, v110, v12 op_sel:[0,1,0] op_sel_hi:[0,1,0]
	v_fma_mix_f32 v12, v8, v111, v12 op_sel_hi:[0,1,0]
	v_fma_mix_f32 v12, v9, v111, v12 op_sel:[0,1,0] op_sel_hi:[0,1,0]
	ds_read_b128 v[36:39], v10 offset:38144
	ds_read_b128 v[44:47], v10 offset:38656
	ds_read_b128 v[40:43], v10 offset:38400
	v_fma_mix_f32 v54, v6, v90, v180 op_sel_hi:[0,1,0]
	v_fma_mix_f32 v54, v7, v90, v54 op_sel:[0,1,0] op_sel_hi:[0,1,0]
	v_add_f32_dpp v12, v12, v12 row_ror:1 row_mask:0xf bank_mask:0xf bound_ctrl:1
	v_fma_mix_f32 v54, v8, v91, v54 op_sel_hi:[0,1,0]
	v_fma_mix_f32 v54, v9, v91, v54 op_sel:[0,1,0] op_sel_hi:[0,1,0]
	v_add_f32_dpp v12, v12, v12 row_ror:2 row_mask:0xf bank_mask:0xf bound_ctrl:1
	v_pk_fma_f32 v[48:49], v[118:119], v[68:69], v[6:7] op_sel:[0,1,0]
	v_pk_fma_f32 v[50:51], v[120:121], v[68:69], v[8:9] op_sel:[0,1,0]
	v_add_f32_dpp v12, v12, v12 row_ror:4 row_mask:0xf bank_mask:0xf bound_ctrl:1
	v_add_f32_dpp v133, v133, v133 row_ror:8 row_mask:0xf bank_mask:0xc
	v_add_f32_dpp v133, v125, v125 row_ror:8 row_mask:0xf bank_mask:0x3
	v_add_f32_dpp v134, v134, v134 row_ror:8 row_mask:0xf bank_mask:0xc
	v_add_f32_dpp v12, v12, v12 row_ror:8 row_mask:0xf bank_mask:0xf bound_ctrl:1
	v_pk_fma_f32 v[6:7], v[114:115], v[12:13], v[48:49] op_sel_hi:[1,0,1] neg_lo:[1,0,0] neg_hi:[1,0,0]
	v_pk_fma_f32 v[8:9], v[116:117], v[12:13], v[50:51] op_sel_hi:[1,0,1] neg_lo:[1,0,0] neg_hi:[1,0,0]
	v_pk_mul_f32 v[6:7], v[6:7], v[106:107]
	v_pk_mul_f32 v[8:9], v[8:9], v[108:109]
	s_waitcnt lgkmcnt(0)
	s_nop 0
	v_fma_mix_f32 v12, v6, v20, v180 op_sel_hi:[0,1,0]
	v_fma_mix_f32 v12, v7, v20, v12 op_sel:[0,1,0] op_sel_hi:[0,1,0]
	v_fma_mix_f32 v12, v8, v21, v12 op_sel_hi:[0,1,0]
	v_fma_mix_f32 v12, v9, v21, v12 op_sel:[0,1,0] op_sel_hi:[0,1,0]
	ds_read_b128 v[88:91], v10 offset:39168
	ds_read_b128 v[96:99], v10 offset:39680
	ds_read_b128 v[92:95], v10 offset:39424
	v_fma_mix_f32 v55, v6, v112, v180 op_sel_hi:[0,1,0]
	v_fma_mix_f32 v55, v7, v112, v55 op_sel:[0,1,0] op_sel_hi:[0,1,0]
	v_add_f32_dpp v12, v12, v12 row_ror:1 row_mask:0xf bank_mask:0xf bound_ctrl:1
	v_fma_mix_f32 v55, v8, v113, v55 op_sel_hi:[0,1,0]
	v_fma_mix_f32 v55, v9, v113, v55 op_sel:[0,1,0] op_sel_hi:[0,1,0]
	v_add_f32_dpp v12, v12, v12 row_ror:2 row_mask:0xf bank_mask:0xf bound_ctrl:1
	v_pk_fma_f32 v[48:49], v[28:29], v[70:71], v[6:7] op_sel_hi:[1,0,1]
	v_pk_fma_f32 v[50:51], v[30:31], v[70:71], v[8:9] op_sel_hi:[1,0,1]
	v_add_f32_dpp v12, v12, v12 row_ror:4 row_mask:0xf bank_mask:0xf bound_ctrl:1
	v_add_f32_dpp v134, v126, v126 row_ror:8 row_mask:0xf bank_mask:0x3
	v_add_f32_dpp v135, v135, v135 row_ror:8 row_mask:0xf bank_mask:0xc
	v_add_f32_dpp v135, v127, v127 row_ror:8 row_mask:0xf bank_mask:0x3
	v_add_f32_dpp v12, v12, v12 row_ror:8 row_mask:0xf bank_mask:0xf bound_ctrl:1
	v_pk_fma_f32 v[6:7], v[24:25], v[12:13], v[48:49] op_sel_hi:[1,0,1] neg_lo:[1,0,0] neg_hi:[1,0,0]
	v_pk_fma_f32 v[8:9], v[26:27], v[12:13], v[50:51] op_sel_hi:[1,0,1] neg_lo:[1,0,0] neg_hi:[1,0,0]
	v_fma_mix_f32 v12, v6, v36, v180 op_sel_hi:[0,1,0]
	v_fma_mix_f32 v12, v7, v36, v12 op_sel:[0,1,0] op_sel_hi:[0,1,0]
	v_fma_mix_f32 v12, v8, v37, v12 op_sel_hi:[0,1,0]
	v_fma_mix_f32 v12, v9, v37, v12 op_sel:[0,1,0] op_sel_hi:[0,1,0]
	ds_read_b128 v[110:113], v10 offset:40192
	ds_read_b128 v[106:109], v10 offset:39936
	ds_read_b128 v[118:121], v10 offset:40704
	ds_read_b128 v[114:117], v10 offset:40448
	ds_read_b128 v[66:69], v11 offset:2560
	v_fma_mix_f32 v56, v6, v22, v180 op_sel_hi:[0,1,0]
	v_fma_mix_f32 v56, v7, v22, v56 op_sel:[0,1,0] op_sel_hi:[0,1,0]
	v_add_f32_dpp v12, v12, v12 row_ror:1 row_mask:0xf bank_mask:0xf bound_ctrl:1
	v_fma_mix_f32 v56, v8, v23, v56 op_sel_hi:[0,1,0]
	v_fma_mix_f32 v56, v9, v23, v56 op_sel:[0,1,0] op_sel_hi:[0,1,0]
	v_add_f32_dpp v12, v12, v12 row_ror:2 row_mask:0xf bank_mask:0xf bound_ctrl:1
	v_pk_fma_f32 v[48:49], v[44:45], v[70:71], v[6:7] op_sel:[0,1,0]
	v_pk_fma_f32 v[50:51], v[46:47], v[70:71], v[8:9] op_sel:[0,1,0]
	v_add_f32_dpp v12, v12, v12 row_ror:4 row_mask:0xf bank_mask:0xf bound_ctrl:1
	v_add_f32_dpp v136, v136, v136 row_ror:8 row_mask:0xf bank_mask:0xc
	v_add_f32_dpp v136, v128, v128 row_ror:8 row_mask:0xf bank_mask:0x3
	v_add_f32_dpp v12, v12, v12 row_ror:8 row_mask:0xf bank_mask:0xf bound_ctrl:1
	v_pk_fma_f32 v[6:7], v[40:41], v[12:13], v[48:49] op_sel_hi:[1,0,1] neg_lo:[1,0,0] neg_hi:[1,0,0]
	v_pk_fma_f32 v[8:9], v[42:43], v[12:13], v[50:51] op_sel_hi:[1,0,1] neg_lo:[1,0,0] neg_hi:[1,0,0]
	s_waitcnt lgkmcnt(1)
	s_nop 0
	v_fma_mix_f32 v12, v6, v88, v180 op_sel_hi:[0,1,0]
	v_fma_mix_f32 v12, v7, v88, v12 op_sel:[0,1,0] op_sel_hi:[0,1,0]
	v_fma_mix_f32 v12, v8, v89, v12 op_sel_hi:[0,1,0]
	v_fma_mix_f32 v12, v9, v89, v12 op_sel:[0,1,0] op_sel_hi:[0,1,0]
	ds_read_b128 v[20:23], v10 offset:41216
	ds_read_b128 v[28:31], v10 offset:41728
	ds_read_b128 v[24:27], v10 offset:41472
	v_fma_mix_f32 v57, v6, v38, v180 op_sel_hi:[0,1,0]
	v_fma_mix_f32 v57, v7, v38, v57 op_sel:[0,1,0] op_sel_hi:[0,1,0]
	v_add_f32_dpp v12, v12, v12 row_ror:1 row_mask:0xf bank_mask:0xf bound_ctrl:1
	v_fma_mix_f32 v57, v8, v39, v57 op_sel_hi:[0,1,0]
	v_fma_mix_f32 v57, v9, v39, v57 op_sel:[0,1,0] op_sel_hi:[0,1,0]
	v_add_f32_dpp v12, v12, v12 row_ror:2 row_mask:0xf bank_mask:0xf bound_ctrl:1
	v_pk_fma_f32 v[48:49], v[96:97], v[72:73], v[6:7] op_sel_hi:[1,0,1]
	v_pk_fma_f32 v[50:51], v[98:99], v[72:73], v[8:9] op_sel_hi:[1,0,1]
	v_add_f32_dpp v12, v12, v12 row_ror:4 row_mask:0xf bank_mask:0xf bound_ctrl:1
	v_add_f32_dpp v137, v137, v137 row_ror:8 row_mask:0xf bank_mask:0xc
	v_add_f32_dpp v137, v129, v129 row_ror:8 row_mask:0xf bank_mask:0x3
	v_add_f32_dpp v12, v12, v12 row_ror:8 row_mask:0xf bank_mask:0xf bound_ctrl:1
	v_pk_fma_f32 v[6:7], v[92:93], v[12:13], v[48:49] op_sel_hi:[1,0,1] neg_lo:[1,0,0] neg_hi:[1,0,0]
	v_pk_fma_f32 v[8:9], v[94:95], v[12:13], v[50:51] op_sel_hi:[1,0,1] neg_lo:[1,0,0] neg_hi:[1,0,0]
	v_fma_mix_f32 v12, v6, v110, v180 op_sel_hi:[0,1,0]
	v_fma_mix_f32 v12, v7, v110, v12 op_sel:[0,1,0] op_sel_hi:[0,1,0]
	v_fma_mix_f32 v12, v8, v111, v12 op_sel_hi:[0,1,0]
	v_fma_mix_f32 v12, v9, v111, v12 op_sel:[0,1,0] op_sel_hi:[0,1,0]
	ds_read_b128 v[36:39], v10 offset:42240
	ds_read_b128 v[44:47], v10 offset:42752
	ds_read_b128 v[40:43], v10 offset:42496
	v_fma_mix_f32 v81, v6, v90, v180 op_sel_hi:[0,1,0]
	v_fma_mix_f32 v81, v7, v90, v81 op_sel:[0,1,0] op_sel_hi:[0,1,0]
	v_add_f32_dpp v12, v12, v12 row_ror:1 row_mask:0xf bank_mask:0xf bound_ctrl:1
	v_fma_mix_f32 v81, v8, v91, v81 op_sel_hi:[0,1,0]
	v_fma_mix_f32 v81, v9, v91, v81 op_sel:[0,1,0] op_sel_hi:[0,1,0]
	v_add_f32_dpp v12, v12, v12 row_ror:2 row_mask:0xf bank_mask:0xf bound_ctrl:1
	v_pk_fma_f32 v[48:49], v[118:119], v[72:73], v[6:7] op_sel:[0,1,0]
	v_pk_fma_f32 v[50:51], v[120:121], v[72:73], v[8:9] op_sel:[0,1,0]
	v_add_f32_dpp v12, v12, v12 row_ror:4 row_mask:0xf bank_mask:0xf bound_ctrl:1
	v_add_f32_dpp v134, v134, v134 row_ror:4 row_mask:0xf bank_mask:0xa
	v_add_f32_dpp v134, v130, v130 row_ror:12 row_mask:0xf bank_mask:0x5
	v_add_f32_dpp v135, v135, v135 row_ror:4 row_mask:0xf bank_mask:0xa
	v_add_f32_dpp v12, v12, v12 row_ror:8 row_mask:0xf bank_mask:0xf bound_ctrl:1
	v_pk_fma_f32 v[6:7], v[114:115], v[12:13], v[48:49] op_sel_hi:[1,0,1] neg_lo:[1,0,0] neg_hi:[1,0,0]
	v_pk_fma_f32 v[8:9], v[116:117], v[12:13], v[50:51] op_sel_hi:[1,0,1] neg_lo:[1,0,0] neg_hi:[1,0,0]
	v_pk_mul_f32 v[6:7], v[6:7], v[106:107]
	v_pk_mul_f32 v[8:9], v[8:9], v[108:109]
	s_waitcnt lgkmcnt(0)
	s_nop 0
	v_fma_mix_f32 v12, v6, v20, v180 op_sel_hi:[0,1,0]
	v_fma_mix_f32 v12, v7, v20, v12 op_sel:[0,1,0] op_sel_hi:[0,1,0]
	v_fma_mix_f32 v12, v8, v21, v12 op_sel_hi:[0,1,0]
	v_fma_mix_f32 v12, v9, v21, v12 op_sel:[0,1,0] op_sel_hi:[0,1,0]
	ds_read_b128 v[88:91], v10 offset:43264
	ds_read_b128 v[96:99], v10 offset:43776
	ds_read_b128 v[92:95], v10 offset:43520
	v_fma_mix_f32 v82, v6, v112, v180 op_sel_hi:[0,1,0]
	v_fma_mix_f32 v82, v7, v112, v82 op_sel:[0,1,0] op_sel_hi:[0,1,0]
	v_add_f32_dpp v12, v12, v12 row_ror:1 row_mask:0xf bank_mask:0xf bound_ctrl:1
	v_fma_mix_f32 v82, v8, v113, v82 op_sel_hi:[0,1,0]
	v_fma_mix_f32 v82, v9, v113, v82 op_sel:[0,1,0] op_sel_hi:[0,1,0]
	v_add_f32_dpp v12, v12, v12 row_ror:2 row_mask:0xf bank_mask:0xf bound_ctrl:1
	v_pk_fma_f32 v[48:49], v[28:29], v[66:67], v[6:7] op_sel_hi:[1,0,1]
	v_pk_fma_f32 v[50:51], v[30:31], v[66:67], v[8:9] op_sel_hi:[1,0,1]
	v_add_f32_dpp v12, v12, v12 row_ror:4 row_mask:0xf bank_mask:0xf bound_ctrl:1
	v_add_f32_dpp v135, v131, v131 row_ror:12 row_mask:0xf bank_mask:0x5
	v_add_f32_dpp v136, v136, v136 row_ror:4 row_mask:0xf bank_mask:0xa
	v_add_f32_dpp v136, v132, v132 row_ror:12 row_mask:0xf bank_mask:0x5
	v_add_f32_dpp v12, v12, v12 row_ror:8 row_mask:0xf bank_mask:0xf bound_ctrl:1
	v_pk_fma_f32 v[6:7], v[24:25], v[12:13], v[48:49] op_sel_hi:[1,0,1] neg_lo:[1,0,0] neg_hi:[1,0,0]
	v_pk_fma_f32 v[8:9], v[26:27], v[12:13], v[50:51] op_sel_hi:[1,0,1] neg_lo:[1,0,0] neg_hi:[1,0,0]
	v_fma_mix_f32 v12, v6, v36, v180 op_sel_hi:[0,1,0]
	v_fma_mix_f32 v12, v7, v36, v12 op_sel:[0,1,0] op_sel_hi:[0,1,0]
	v_fma_mix_f32 v12, v8, v37, v12 op_sel_hi:[0,1,0]
	v_fma_mix_f32 v12, v9, v37, v12 op_sel:[0,1,0] op_sel_hi:[0,1,0]
	ds_read_b128 v[110:113], v10 offset:44288
	ds_read_b128 v[106:109], v10 offset:44032
	ds_read_b128 v[118:121], v10 offset:44800
	ds_read_b128 v[114:117], v10 offset:44544
	ds_read_b128 v[70:73], v11 offset:2816
	v_fma_mix_f32 v83, v6, v22, v180 op_sel_hi:[0,1,0]
	v_fma_mix_f32 v83, v7, v22, v83 op_sel:[0,1,0] op_sel_hi:[0,1,0]
	v_add_f32_dpp v12, v12, v12 row_ror:1 row_mask:0xf bank_mask:0xf bound_ctrl:1
	v_fma_mix_f32 v83, v8, v23, v83 op_sel_hi:[0,1,0]
	v_fma_mix_f32 v83, v9, v23, v83 op_sel:[0,1,0] op_sel_hi:[0,1,0]
	v_add_f32_dpp v12, v12, v12 row_ror:2 row_mask:0xf bank_mask:0xf bound_ctrl:1
	v_pk_fma_f32 v[48:49], v[44:45], v[66:67], v[6:7] op_sel:[0,1,0]
	v_pk_fma_f32 v[50:51], v[46:47], v[66:67], v[8:9] op_sel:[0,1,0]
	v_add_f32_dpp v12, v12, v12 row_ror:4 row_mask:0xf bank_mask:0xf bound_ctrl:1
	v_add_f32_dpp v137, v137, v137 row_ror:4 row_mask:0xf bank_mask:0xa
	v_add_f32_dpp v137, v133, v133 row_ror:12 row_mask:0xf bank_mask:0x5
	v_add_f32_dpp v12, v12, v12 row_ror:8 row_mask:0xf bank_mask:0xf bound_ctrl:1
	v_pk_fma_f32 v[6:7], v[40:41], v[12:13], v[48:49] op_sel_hi:[1,0,1] neg_lo:[1,0,0] neg_hi:[1,0,0]
	v_pk_fma_f32 v[8:9], v[42:43], v[12:13], v[50:51] op_sel_hi:[1,0,1] neg_lo:[1,0,0] neg_hi:[1,0,0]
	s_waitcnt lgkmcnt(1)
	s_nop 0
	v_fma_mix_f32 v12, v6, v88, v180 op_sel_hi:[0,1,0]
	v_fma_mix_f32 v12, v7, v88, v12 op_sel:[0,1,0] op_sel_hi:[0,1,0]
	v_fma_mix_f32 v12, v8, v89, v12 op_sel_hi:[0,1,0]
	v_fma_mix_f32 v12, v9, v89, v12 op_sel:[0,1,0] op_sel_hi:[0,1,0]
	ds_read_b128 v[20:23], v10 offset:45312
	ds_read_b128 v[28:31], v10 offset:45824
	ds_read_b128 v[24:27], v10 offset:45568
	v_fma_mix_f32 v100, v6, v38, v180 op_sel_hi:[0,1,0]
	v_fma_mix_f32 v100, v7, v38, v100 op_sel:[0,1,0] op_sel_hi:[0,1,0]
	v_add_f32_dpp v12, v12, v12 row_ror:1 row_mask:0xf bank_mask:0xf bound_ctrl:1
	v_fma_mix_f32 v100, v8, v39, v100 op_sel_hi:[0,1,0]
	v_fma_mix_f32 v100, v9, v39, v100 op_sel:[0,1,0] op_sel_hi:[0,1,0]
	v_add_f32_dpp v12, v12, v12 row_ror:2 row_mask:0xf bank_mask:0xf bound_ctrl:1
	v_pk_fma_f32 v[48:49], v[96:97], v[68:69], v[6:7] op_sel_hi:[1,0,1]
	v_pk_fma_f32 v[50:51], v[98:99], v[68:69], v[8:9] op_sel_hi:[1,0,1]
	v_add_f32_dpp v12, v12, v12 row_ror:4 row_mask:0xf bank_mask:0xf bound_ctrl:1
	v_cndmask_b32_e64 v62, v136, v134, s[38:39]
	v_cndmask_b32_e64 v63, v134, v136, s[38:39]
	v_add_f32_dpp v12, v12, v12 row_ror:8 row_mask:0xf bank_mask:0xf bound_ctrl:1
	v_pk_fma_f32 v[6:7], v[92:93], v[12:13], v[48:49] op_sel_hi:[1,0,1] neg_lo:[1,0,0] neg_hi:[1,0,0]
	v_pk_fma_f32 v[8:9], v[94:95], v[12:13], v[50:51] op_sel_hi:[1,0,1] neg_lo:[1,0,0] neg_hi:[1,0,0]
	v_fma_mix_f32 v12, v6, v110, v180 op_sel_hi:[0,1,0]
	v_fma_mix_f32 v12, v7, v110, v12 op_sel:[0,1,0] op_sel_hi:[0,1,0]
	v_fma_mix_f32 v12, v8, v111, v12 op_sel_hi:[0,1,0]
	v_fma_mix_f32 v12, v9, v111, v12 op_sel:[0,1,0] op_sel_hi:[0,1,0]
	ds_read_b128 v[36:39], v10 offset:46336
	ds_read_b128 v[44:47], v10 offset:46848
	ds_read_b128 v[40:43], v10 offset:46592
	v_fma_mix_f32 v101, v6, v90, v180 op_sel_hi:[0,1,0]
	v_fma_mix_f32 v101, v7, v90, v101 op_sel:[0,1,0] op_sel_hi:[0,1,0]
	v_add_f32_dpp v12, v12, v12 row_ror:1 row_mask:0xf bank_mask:0xf bound_ctrl:1
	v_fma_mix_f32 v101, v8, v91, v101 op_sel_hi:[0,1,0]
	v_fma_mix_f32 v101, v9, v91, v101 op_sel:[0,1,0] op_sel_hi:[0,1,0]
	v_add_f32_dpp v12, v12, v12 row_ror:2 row_mask:0xf bank_mask:0xf bound_ctrl:1
	v_pk_fma_f32 v[48:49], v[118:119], v[68:69], v[6:7] op_sel:[0,1,0]
	v_pk_fma_f32 v[50:51], v[120:121], v[68:69], v[8:9] op_sel:[0,1,0]
	v_add_f32_dpp v12, v12, v12 row_ror:4 row_mask:0xf bank_mask:0xf bound_ctrl:1
	v_cndmask_b32_e64 v64, v137, v135, s[38:39]
	v_cndmask_b32_e64 v65, v135, v137, s[38:39]
	v_add_f32_dpp v12, v12, v12 row_ror:8 row_mask:0xf bank_mask:0xf bound_ctrl:1
	v_pk_fma_f32 v[6:7], v[114:115], v[12:13], v[48:49] op_sel_hi:[1,0,1] neg_lo:[1,0,0] neg_hi:[1,0,0]
	v_pk_fma_f32 v[8:9], v[116:117], v[12:13], v[50:51] op_sel_hi:[1,0,1] neg_lo:[1,0,0] neg_hi:[1,0,0]
	v_pk_mul_f32 v[6:7], v[6:7], v[106:107]
	v_pk_mul_f32 v[8:9], v[8:9], v[108:109]
	s_waitcnt lgkmcnt(0)
	s_nop 0
	v_fma_mix_f32 v12, v6, v20, v180 op_sel_hi:[0,1,0]
	v_fma_mix_f32 v12, v7, v20, v12 op_sel:[0,1,0] op_sel_hi:[0,1,0]
	v_fma_mix_f32 v12, v8, v21, v12 op_sel_hi:[0,1,0]
	v_fma_mix_f32 v12, v9, v21, v12 op_sel:[0,1,0] op_sel_hi:[0,1,0]
	ds_read_b128 v[88:91], v10 offset:47360
	ds_read_b128 v[96:99], v10 offset:47872
	ds_read_b128 v[92:95], v10 offset:47616
	v_fma_mix_f32 v102, v6, v112, v180 op_sel_hi:[0,1,0]
	v_fma_mix_f32 v102, v7, v112, v102 op_sel:[0,1,0] op_sel_hi:[0,1,0]
	v_add_f32_dpp v12, v12, v12 row_ror:1 row_mask:0xf bank_mask:0xf bound_ctrl:1
	v_fma_mix_f32 v102, v8, v113, v102 op_sel_hi:[0,1,0]
	v_fma_mix_f32 v102, v9, v113, v102 op_sel:[0,1,0] op_sel_hi:[0,1,0]
	v_add_f32_dpp v12, v12, v12 row_ror:2 row_mask:0xf bank_mask:0xf bound_ctrl:1
	v_pk_fma_f32 v[48:49], v[28:29], v[70:71], v[6:7] op_sel_hi:[1,0,1]
	v_pk_fma_f32 v[50:51], v[30:31], v[70:71], v[8:9] op_sel_hi:[1,0,1]
	v_add_f32_dpp v12, v12, v12 row_ror:4 row_mask:0xf bank_mask:0xf bound_ctrl:1
	v_add_f32_dpp v62, v63, v62 quad_perm:[2,3,0,1] row_mask:0xf bank_mask:0xf bound_ctrl:1
	v_add_f32_dpp v63, v65, v64 quad_perm:[2,3,0,1] row_mask:0xf bank_mask:0xf bound_ctrl:1
	v_add_f32_dpp v12, v12, v12 row_ror:8 row_mask:0xf bank_mask:0xf bound_ctrl:1
	v_pk_fma_f32 v[6:7], v[24:25], v[12:13], v[48:49] op_sel_hi:[1,0,1] neg_lo:[1,0,0] neg_hi:[1,0,0]
	v_pk_fma_f32 v[8:9], v[26:27], v[12:13], v[50:51] op_sel_hi:[1,0,1] neg_lo:[1,0,0] neg_hi:[1,0,0]
	v_fma_mix_f32 v12, v6, v36, v180 op_sel_hi:[0,1,0]
	v_fma_mix_f32 v12, v7, v36, v12 op_sel:[0,1,0] op_sel_hi:[0,1,0]
	v_fma_mix_f32 v12, v8, v37, v12 op_sel_hi:[0,1,0]
	v_fma_mix_f32 v12, v9, v37, v12 op_sel:[0,1,0] op_sel_hi:[0,1,0]
	ds_read_b128 v[110:113], v10 offset:48384
	ds_read_b128 v[106:109], v10 offset:48128
	ds_read_b128 v[118:121], v10 offset:48896
	ds_read_b128 v[114:117], v10 offset:48640
	ds_read_b128 v[66:69], v11 offset:3072
	v_fma_mix_f32 v103, v6, v22, v180 op_sel_hi:[0,1,0]
	v_fma_mix_f32 v103, v7, v22, v103 op_sel:[0,1,0] op_sel_hi:[0,1,0]
	v_add_f32_dpp v12, v12, v12 row_ror:1 row_mask:0xf bank_mask:0xf bound_ctrl:1
	v_fma_mix_f32 v103, v8, v23, v103 op_sel_hi:[0,1,0]
	v_fma_mix_f32 v103, v9, v23, v103 op_sel:[0,1,0] op_sel_hi:[0,1,0]
	v_add_f32_dpp v12, v12, v12 row_ror:2 row_mask:0xf bank_mask:0xf bound_ctrl:1
	v_pk_fma_f32 v[48:49], v[44:45], v[70:71], v[6:7] op_sel:[0,1,0]
	v_pk_fma_f32 v[50:51], v[46:47], v[70:71], v[8:9] op_sel:[0,1,0]
	v_add_f32_dpp v12, v12, v12 row_ror:4 row_mask:0xf bank_mask:0xf bound_ctrl:1
	v_cndmask_b32_e64 v65, v63, v62, s[40:41]
	v_cndmask_b32_e64 v62, v62, v63, s[40:41]
	v_add_f32_dpp v12, v12, v12 row_ror:8 row_mask:0xf bank_mask:0xf bound_ctrl:1
	v_pk_fma_f32 v[6:7], v[40:41], v[12:13], v[48:49] op_sel_hi:[1,0,1] neg_lo:[1,0,0] neg_hi:[1,0,0]
	v_pk_fma_f32 v[8:9], v[42:43], v[12:13], v[50:51] op_sel_hi:[1,0,1] neg_lo:[1,0,0] neg_hi:[1,0,0]
	s_waitcnt lgkmcnt(1)
	s_nop 0
	v_fma_mix_f32 v12, v6, v88, v180 op_sel_hi:[0,1,0]
	v_fma_mix_f32 v12, v7, v88, v12 op_sel:[0,1,0] op_sel_hi:[0,1,0]
	v_fma_mix_f32 v12, v8, v89, v12 op_sel_hi:[0,1,0]
	v_fma_mix_f32 v12, v9, v89, v12 op_sel:[0,1,0] op_sel_hi:[0,1,0]
	ds_read_b128 v[20:23], v10 offset:49408
	ds_read_b128 v[28:31], v10 offset:49920
	ds_read_b128 v[24:27], v10 offset:49664
	v_fma_mix_f32 v104, v6, v38, v180 op_sel_hi:[0,1,0]
	v_fma_mix_f32 v104, v7, v38, v104 op_sel:[0,1,0] op_sel_hi:[0,1,0]
	v_add_f32_dpp v12, v12, v12 row_ror:1 row_mask:0xf bank_mask:0xf bound_ctrl:1
	v_fma_mix_f32 v104, v8, v39, v104 op_sel_hi:[0,1,0]
	v_fma_mix_f32 v104, v9, v39, v104 op_sel:[0,1,0] op_sel_hi:[0,1,0]
	v_add_f32_dpp v12, v12, v12 row_ror:2 row_mask:0xf bank_mask:0xf bound_ctrl:1
	v_pk_fma_f32 v[48:49], v[96:97], v[72:73], v[6:7] op_sel_hi:[1,0,1]
	v_pk_fma_f32 v[50:51], v[98:99], v[72:73], v[8:9] op_sel_hi:[1,0,1]
	v_add_f32_dpp v12, v12, v12 row_ror:4 row_mask:0xf bank_mask:0xf bound_ctrl:1
	v_add_f32_dpp v62, v62, v65 quad_perm:[1,0,3,2] row_mask:0xf bank_mask:0xf bound_ctrl:1
	v_cvt_pk_bf16_f32 v62, v62, v62
	v_add_f32_dpp v12, v12, v12 row_ror:8 row_mask:0xf bank_mask:0xf bound_ctrl:1
	v_pk_fma_f32 v[6:7], v[92:93], v[12:13], v[48:49] op_sel_hi:[1,0,1] neg_lo:[1,0,0] neg_hi:[1,0,0]
	v_pk_fma_f32 v[8:9], v[94:95], v[12:13], v[50:51] op_sel_hi:[1,0,1] neg_lo:[1,0,0] neg_hi:[1,0,0]
	v_fma_mix_f32 v12, v6, v110, v180 op_sel_hi:[0,1,0]
	v_fma_mix_f32 v12, v7, v110, v12 op_sel:[0,1,0] op_sel_hi:[0,1,0]
	v_fma_mix_f32 v12, v8, v111, v12 op_sel_hi:[0,1,0]
	v_fma_mix_f32 v12, v9, v111, v12 op_sel:[0,1,0] op_sel_hi:[0,1,0]
	ds_read_b128 v[36:39], v10 offset:50432
	ds_read_b128 v[44:47], v10 offset:50944
	ds_read_b128 v[40:43], v10 offset:50688
	v_fma_mix_f32 v105, v6, v90, v180 op_sel_hi:[0,1,0]
	v_fma_mix_f32 v105, v7, v90, v105 op_sel:[0,1,0] op_sel_hi:[0,1,0]
	v_add_f32_dpp v12, v12, v12 row_ror:1 row_mask:0xf bank_mask:0xf bound_ctrl:1
	v_fma_mix_f32 v105, v8, v91, v105 op_sel_hi:[0,1,0]
	v_fma_mix_f32 v105, v9, v91, v105 op_sel:[0,1,0] op_sel_hi:[0,1,0]
	v_add_f32_dpp v12, v12, v12 row_ror:2 row_mask:0xf bank_mask:0xf bound_ctrl:1
	v_pk_fma_f32 v[48:49], v[118:119], v[72:73], v[6:7] op_sel:[0,1,0]
	v_pk_fma_f32 v[50:51], v[120:121], v[72:73], v[8:9] op_sel:[0,1,0]
	v_add_f32_dpp v12, v12, v12 row_ror:4 row_mask:0xf bank_mask:0xf bound_ctrl:1
	global_store_short v[2:3], v62, off
	v_lshl_add_u64 v[2:3], v[2:3], 0, s[84:85]
	v_add_f32_dpp v12, v12, v12 row_ror:8 row_mask:0xf bank_mask:0xf bound_ctrl:1
	v_pk_fma_f32 v[6:7], v[114:115], v[12:13], v[48:49] op_sel_hi:[1,0,1] neg_lo:[1,0,0] neg_hi:[1,0,0]
	v_pk_fma_f32 v[8:9], v[116:117], v[12:13], v[50:51] op_sel_hi:[1,0,1] neg_lo:[1,0,0] neg_hi:[1,0,0]
	v_pk_mul_f32 v[6:7], v[6:7], v[106:107]
	v_pk_mul_f32 v[8:9], v[8:9], v[108:109]
	s_waitcnt lgkmcnt(0)
	s_nop 0
	v_fma_mix_f32 v12, v6, v20, v180 op_sel_hi:[0,1,0]
	v_fma_mix_f32 v12, v7, v20, v12 op_sel:[0,1,0] op_sel_hi:[0,1,0]
	v_fma_mix_f32 v12, v8, v21, v12 op_sel_hi:[0,1,0]
	v_fma_mix_f32 v12, v9, v21, v12 op_sel:[0,1,0] op_sel_hi:[0,1,0]
	ds_read_b128 v[88:91], v10 offset:51456
	ds_read_b128 v[96:99], v10 offset:51968
	ds_read_b128 v[92:95], v10 offset:51712
	v_fma_mix_f32 v61, v6, v112, v180 op_sel_hi:[0,1,0]
	v_fma_mix_f32 v61, v7, v112, v61 op_sel:[0,1,0] op_sel_hi:[0,1,0]
	v_add_f32_dpp v12, v12, v12 row_ror:1 row_mask:0xf bank_mask:0xf bound_ctrl:1
	v_fma_mix_f32 v61, v8, v113, v61 op_sel_hi:[0,1,0]
	v_fma_mix_f32 v61, v9, v113, v61 op_sel:[0,1,0] op_sel_hi:[0,1,0]
	v_add_f32_dpp v12, v12, v12 row_ror:2 row_mask:0xf bank_mask:0xf bound_ctrl:1
	v_pk_fma_f32 v[48:49], v[28:29], v[66:67], v[6:7] op_sel_hi:[1,0,1]
	v_pk_fma_f32 v[50:51], v[30:31], v[66:67], v[8:9] op_sel_hi:[1,0,1]
	v_add_f32_dpp v12, v12, v12 row_ror:4 row_mask:0xf bank_mask:0xf bound_ctrl:1
	s_nop 1
	s_nop 0
	v_add_f32_dpp v12, v12, v12 row_ror:8 row_mask:0xf bank_mask:0xf bound_ctrl:1
	v_pk_fma_f32 v[6:7], v[24:25], v[12:13], v[48:49] op_sel_hi:[1,0,1] neg_lo:[1,0,0] neg_hi:[1,0,0]
	v_pk_fma_f32 v[8:9], v[26:27], v[12:13], v[50:51] op_sel_hi:[1,0,1] neg_lo:[1,0,0] neg_hi:[1,0,0]
	v_fma_mix_f32 v12, v6, v36, v180 op_sel_hi:[0,1,0]
	v_fma_mix_f32 v12, v7, v36, v12 op_sel:[0,1,0] op_sel_hi:[0,1,0]
	v_fma_mix_f32 v12, v8, v37, v12 op_sel_hi:[0,1,0]
	v_fma_mix_f32 v12, v9, v37, v12 op_sel:[0,1,0] op_sel_hi:[0,1,0]
	ds_read_b128 v[110:113], v10 offset:52480
	ds_read_b128 v[106:109], v10 offset:52224
	ds_read_b128 v[118:121], v10 offset:52992
	ds_read_b128 v[114:117], v10 offset:52736
	ds_read_b128 v[70:73], v11 offset:3328
	v_fma_mix_f32 v122, v6, v22, v180 op_sel_hi:[0,1,0]
	v_fma_mix_f32 v122, v7, v22, v122 op_sel:[0,1,0] op_sel_hi:[0,1,0]
	v_add_f32_dpp v12, v12, v12 row_ror:1 row_mask:0xf bank_mask:0xf bound_ctrl:1
	v_fma_mix_f32 v122, v8, v23, v122 op_sel_hi:[0,1,0]
	v_fma_mix_f32 v122, v9, v23, v122 op_sel:[0,1,0] op_sel_hi:[0,1,0]
	v_add_f32_dpp v12, v12, v12 row_ror:2 row_mask:0xf bank_mask:0xf bound_ctrl:1
	v_pk_fma_f32 v[48:49], v[44:45], v[66:67], v[6:7] op_sel:[0,1,0]
	v_pk_fma_f32 v[50:51], v[46:47], v[66:67], v[8:9] op_sel:[0,1,0]
	v_add_f32_dpp v12, v12, v12 row_ror:4 row_mask:0xf bank_mask:0xf bound_ctrl:1
	v_add_f32_dpp v83, v83, v83 row_ror:8 row_mask:0xf bank_mask:0xc
	v_add_f32_dpp v83, v52, v52 row_ror:8 row_mask:0xf bank_mask:0x3
	v_add_f32_dpp v100, v100, v100 row_ror:8 row_mask:0xf bank_mask:0xc
	v_add_f32_dpp v12, v12, v12 row_ror:8 row_mask:0xf bank_mask:0xf bound_ctrl:1
	v_pk_fma_f32 v[6:7], v[40:41], v[12:13], v[48:49] op_sel_hi:[1,0,1] neg_lo:[1,0,0] neg_hi:[1,0,0]
	v_pk_fma_f32 v[8:9], v[42:43], v[12:13], v[50:51] op_sel_hi:[1,0,1] neg_lo:[1,0,0] neg_hi:[1,0,0]
	s_waitcnt lgkmcnt(1)
	s_nop 0
	v_fma_mix_f32 v12, v6, v88, v180 op_sel_hi:[0,1,0]
	v_fma_mix_f32 v12, v7, v88, v12 op_sel:[0,1,0] op_sel_hi:[0,1,0]
	v_fma_mix_f32 v12, v8, v89, v12 op_sel_hi:[0,1,0]
	v_fma_mix_f32 v12, v9, v89, v12 op_sel:[0,1,0] op_sel_hi:[0,1,0]
	ds_read_b128 v[20:23], v10 offset:53504
	ds_read_b128 v[28:31], v10 offset:54016
	ds_read_b128 v[24:27], v10 offset:53760
	v_fma_mix_f32 v123, v6, v38, v180 op_sel_hi:[0,1,0]
	v_fma_mix_f32 v123, v7, v38, v123 op_sel:[0,1,0] op_sel_hi:[0,1,0]
	v_add_f32_dpp v12, v12, v12 row_ror:1 row_mask:0xf bank_mask:0xf bound_ctrl:1
	v_fma_mix_f32 v123, v8, v39, v123 op_sel_hi:[0,1,0]
	v_fma_mix_f32 v123, v9, v39, v123 op_sel:[0,1,0] op_sel_hi:[0,1,0]
	v_add_f32_dpp v12, v12, v12 row_ror:2 row_mask:0xf bank_mask:0xf bound_ctrl:1
	v_pk_fma_f32 v[48:49], v[96:97], v[68:69], v[6:7] op_sel_hi:[1,0,1]
	v_pk_fma_f32 v[50:51], v[98:99], v[68:69], v[8:9] op_sel_hi:[1,0,1]
	v_add_f32_dpp v12, v12, v12 row_ror:4 row_mask:0xf bank_mask:0xf bound_ctrl:1
	v_add_f32_dpp v100, v53, v53 row_ror:8 row_mask:0xf bank_mask:0x3
	v_add_f32_dpp v101, v101, v101 row_ror:8 row_mask:0xf bank_mask:0xc
	v_add_f32_dpp v101, v54, v54 row_ror:8 row_mask:0xf bank_mask:0x3
	v_add_f32_dpp v12, v12, v12 row_ror:8 row_mask:0xf bank_mask:0xf bound_ctrl:1
	v_pk_fma_f32 v[6:7], v[92:93], v[12:13], v[48:49] op_sel_hi:[1,0,1] neg_lo:[1,0,0] neg_hi:[1,0,0]
	v_pk_fma_f32 v[8:9], v[94:95], v[12:13], v[50:51] op_sel_hi:[1,0,1] neg_lo:[1,0,0] neg_hi:[1,0,0]
	v_fma_mix_f32 v12, v6, v110, v180 op_sel_hi:[0,1,0]
	v_fma_mix_f32 v12, v7, v110, v12 op_sel:[0,1,0] op_sel_hi:[0,1,0]
	v_fma_mix_f32 v12, v8, v111, v12 op_sel_hi:[0,1,0]
	v_fma_mix_f32 v12, v9, v111, v12 op_sel:[0,1,0] op_sel_hi:[0,1,0]
	ds_read_b128 v[36:39], v10 offset:54528
	ds_read_b128 v[44:47], v10 offset:55040
	ds_read_b128 v[40:43], v10 offset:54784
	v_fma_mix_f32 v124, v6, v90, v180 op_sel_hi:[0,1,0]
	v_fma_mix_f32 v124, v7, v90, v124 op_sel:[0,1,0] op_sel_hi:[0,1,0]
	v_add_f32_dpp v12, v12, v12 row_ror:1 row_mask:0xf bank_mask:0xf bound_ctrl:1
	v_fma_mix_f32 v124, v8, v91, v124 op_sel_hi:[0,1,0]
	v_fma_mix_f32 v124, v9, v91, v124 op_sel:[0,1,0] op_sel_hi:[0,1,0]
	v_add_f32_dpp v12, v12, v12 row_ror:2 row_mask:0xf bank_mask:0xf bound_ctrl:1
	v_pk_fma_f32 v[48:49], v[118:119], v[68:69], v[6:7] op_sel:[0,1,0]
	v_pk_fma_f32 v[50:51], v[120:121], v[68:69], v[8:9] op_sel:[0,1,0]
	v_add_f32_dpp v12, v12, v12 row_ror:4 row_mask:0xf bank_mask:0xf bound_ctrl:1
	v_add_f32_dpp v102, v102, v102 row_ror:8 row_mask:0xf bank_mask:0xc
	v_add_f32_dpp v102, v55, v55 row_ror:8 row_mask:0xf bank_mask:0x3
	v_add_f32_dpp v103, v103, v103 row_ror:8 row_mask:0xf bank_mask:0xc
	v_add_f32_dpp v12, v12, v12 row_ror:8 row_mask:0xf bank_mask:0xf bound_ctrl:1
	v_pk_fma_f32 v[6:7], v[114:115], v[12:13], v[48:49] op_sel_hi:[1,0,1] neg_lo:[1,0,0] neg_hi:[1,0,0]
	v_pk_fma_f32 v[8:9], v[116:117], v[12:13], v[50:51] op_sel_hi:[1,0,1] neg_lo:[1,0,0] neg_hi:[1,0,0]
	v_pk_mul_f32 v[6:7], v[6:7], v[106:107]
	v_pk_mul_f32 v[8:9], v[8:9], v[108:109]
	s_waitcnt lgkmcnt(0)
	s_nop 0
	v_fma_mix_f32 v12, v6, v20, v180 op_sel_hi:[0,1,0]
	v_fma_mix_f32 v12, v7, v20, v12 op_sel:[0,1,0] op_sel_hi:[0,1,0]
	v_fma_mix_f32 v12, v8, v21, v12 op_sel_hi:[0,1,0]
	v_fma_mix_f32 v12, v9, v21, v12 op_sel:[0,1,0] op_sel_hi:[0,1,0]
	ds_read_b128 v[88:91], v10 offset:55552
	ds_read_b128 v[96:99], v10 offset:56064
	ds_read_b128 v[92:95], v10 offset:55808
	v_fma_mix_f32 v125, v6, v112, v180 op_sel_hi:[0,1,0]
	v_fma_mix_f32 v125, v7, v112, v125 op_sel:[0,1,0] op_sel_hi:[0,1,0]
	v_add_f32_dpp v12, v12, v12 row_ror:1 row_mask:0xf bank_mask:0xf bound_ctrl:1
	v_fma_mix_f32 v125, v8, v113, v125 op_sel_hi:[0,1,0]
	v_fma_mix_f32 v125, v9, v113, v125 op_sel:[0,1,0] op_sel_hi:[0,1,0]
	v_add_f32_dpp v12, v12, v12 row_ror:2 row_mask:0xf bank_mask:0xf bound_ctrl:1
	v_pk_fma_f32 v[48:49], v[28:29], v[70:71], v[6:7] op_sel_hi:[1,0,1]
	v_pk_fma_f32 v[50:51], v[30:31], v[70:71], v[8:9] op_sel_hi:[1,0,1]
	v_add_f32_dpp v12, v12, v12 row_ror:4 row_mask:0xf bank_mask:0xf bound_ctrl:1
	v_add_f32_dpp v103, v56, v56 row_ror:8 row_mask:0xf bank_mask:0x3
	v_add_f32_dpp v104, v104, v104 row_ror:8 row_mask:0xf bank_mask:0xc
	v_add_f32_dpp v104, v57, v57 row_ror:8 row_mask:0xf bank_mask:0x3
	v_add_f32_dpp v12, v12, v12 row_ror:8 row_mask:0xf bank_mask:0xf bound_ctrl:1
	v_pk_fma_f32 v[6:7], v[24:25], v[12:13], v[48:49] op_sel_hi:[1,0,1] neg_lo:[1,0,0] neg_hi:[1,0,0]
	v_pk_fma_f32 v[8:9], v[26:27], v[12:13], v[50:51] op_sel_hi:[1,0,1] neg_lo:[1,0,0] neg_hi:[1,0,0]
	v_fma_mix_f32 v12, v6, v36, v180 op_sel_hi:[0,1,0]
	v_fma_mix_f32 v12, v7, v36, v12 op_sel:[0,1,0] op_sel_hi:[0,1,0]
	v_fma_mix_f32 v12, v8, v37, v12 op_sel_hi:[0,1,0]
	v_fma_mix_f32 v12, v9, v37, v12 op_sel:[0,1,0] op_sel_hi:[0,1,0]
	ds_read_b128 v[110:113], v10 offset:56576
	ds_read_b128 v[106:109], v10 offset:56320
	ds_read_b128 v[118:121], v10 offset:57088
	ds_read_b128 v[114:117], v10 offset:56832
	ds_read_b128 v[66:69], v11 offset:3584
	v_fma_mix_f32 v126, v6, v22, v180 op_sel_hi:[0,1,0]
	v_fma_mix_f32 v126, v7, v22, v126 op_sel:[0,1,0] op_sel_hi:[0,1,0]
	v_add_f32_dpp v12, v12, v12 row_ror:1 row_mask:0xf bank_mask:0xf bound_ctrl:1
	v_fma_mix_f32 v126, v8, v23, v126 op_sel_hi:[0,1,0]
	v_fma_mix_f32 v126, v9, v23, v126 op_sel:[0,1,0] op_sel_hi:[0,1,0]
	v_add_f32_dpp v12, v12, v12 row_ror:2 row_mask:0xf bank_mask:0xf bound_ctrl:1
	v_pk_fma_f32 v[48:49], v[44:45], v[70:71], v[6:7] op_sel:[0,1,0]
	v_pk_fma_f32 v[50:51], v[46:47], v[70:71], v[8:9] op_sel:[0,1,0]
	v_add_f32_dpp v12, v12, v12 row_ror:4 row_mask:0xf bank_mask:0xf bound_ctrl:1
	v_add_f32_dpp v105, v105, v105 row_ror:8 row_mask:0xf bank_mask:0xc
	v_add_f32_dpp v105, v81, v81 row_ror:8 row_mask:0xf bank_mask:0x3
	v_add_f32_dpp v12, v12, v12 row_ror:8 row_mask:0xf bank_mask:0xf bound_ctrl:1
	v_pk_fma_f32 v[6:7], v[40:41], v[12:13], v[48:49] op_sel_hi:[1,0,1] neg_lo:[1,0,0] neg_hi:[1,0,0]
	v_pk_fma_f32 v[8:9], v[42:43], v[12:13], v[50:51] op_sel_hi:[1,0,1] neg_lo:[1,0,0] neg_hi:[1,0,0]
	s_waitcnt lgkmcnt(1)
	s_nop 0
	v_fma_mix_f32 v12, v6, v88, v180 op_sel_hi:[0,1,0]
	v_fma_mix_f32 v12, v7, v88, v12 op_sel:[0,1,0] op_sel_hi:[0,1,0]
	v_fma_mix_f32 v12, v8, v89, v12 op_sel_hi:[0,1,0]
	v_fma_mix_f32 v12, v9, v89, v12 op_sel:[0,1,0] op_sel_hi:[0,1,0]
	ds_read_b128 v[20:23], v10 offset:57600
	ds_read_b128 v[28:31], v10 offset:58112
	ds_read_b128 v[24:27], v10 offset:57856
	v_fma_mix_f32 v127, v6, v38, v180 op_sel_hi:[0,1,0]
	v_fma_mix_f32 v127, v7, v38, v127 op_sel:[0,1,0] op_sel_hi:[0,1,0]
	v_add_f32_dpp v12, v12, v12 row_ror:1 row_mask:0xf bank_mask:0xf bound_ctrl:1
	v_fma_mix_f32 v127, v8, v39, v127 op_sel_hi:[0,1,0]
	v_fma_mix_f32 v127, v9, v39, v127 op_sel:[0,1,0] op_sel_hi:[0,1,0]
	v_add_f32_dpp v12, v12, v12 row_ror:2 row_mask:0xf bank_mask:0xf bound_ctrl:1
	v_pk_fma_f32 v[48:49], v[96:97], v[72:73], v[6:7] op_sel_hi:[1,0,1]
	v_pk_fma_f32 v[50:51], v[98:99], v[72:73], v[8:9] op_sel_hi:[1,0,1]
	v_add_f32_dpp v12, v12, v12 row_ror:4 row_mask:0xf bank_mask:0xf bound_ctrl:1
	v_add_f32_dpp v61, v61, v61 row_ror:8 row_mask:0xf bank_mask:0xc
	v_add_f32_dpp v61, v82, v82 row_ror:8 row_mask:0xf bank_mask:0x3
	v_add_f32_dpp v12, v12, v12 row_ror:8 row_mask:0xf bank_mask:0xf bound_ctrl:1
	v_pk_fma_f32 v[6:7], v[92:93], v[12:13], v[48:49] op_sel_hi:[1,0,1] neg_lo:[1,0,0] neg_hi:[1,0,0]
	v_pk_fma_f32 v[8:9], v[94:95], v[12:13], v[50:51] op_sel_hi:[1,0,1] neg_lo:[1,0,0] neg_hi:[1,0,0]
	v_fma_mix_f32 v12, v6, v110, v180 op_sel_hi:[0,1,0]
	v_fma_mix_f32 v12, v7, v110, v12 op_sel:[0,1,0] op_sel_hi:[0,1,0]
	v_fma_mix_f32 v12, v8, v111, v12 op_sel_hi:[0,1,0]
	v_fma_mix_f32 v12, v9, v111, v12 op_sel:[0,1,0] op_sel_hi:[0,1,0]
	ds_read_b128 v[36:39], v10 offset:58624
	ds_read_b128 v[44:47], v10 offset:59136
	ds_read_b128 v[40:43], v10 offset:58880
	v_fma_mix_f32 v128, v6, v90, v180 op_sel_hi:[0,1,0]
	v_fma_mix_f32 v128, v7, v90, v128 op_sel:[0,1,0] op_sel_hi:[0,1,0]
	v_add_f32_dpp v12, v12, v12 row_ror:1 row_mask:0xf bank_mask:0xf bound_ctrl:1
	v_fma_mix_f32 v128, v8, v91, v128 op_sel_hi:[0,1,0]
	v_fma_mix_f32 v128, v9, v91, v128 op_sel:[0,1,0] op_sel_hi:[0,1,0]
	v_add_f32_dpp v12, v12, v12 row_ror:2 row_mask:0xf bank_mask:0xf bound_ctrl:1
	v_pk_fma_f32 v[48:49], v[118:119], v[72:73], v[6:7] op_sel:[0,1,0]
	v_pk_fma_f32 v[50:51], v[120:121], v[72:73], v[8:9] op_sel:[0,1,0]
	v_add_f32_dpp v12, v12, v12 row_ror:4 row_mask:0xf bank_mask:0xf bound_ctrl:1
	v_add_f32_dpp v103, v103, v103 row_ror:4 row_mask:0xf bank_mask:0xa
	v_add_f32_dpp v103, v83, v83 row_ror:12 row_mask:0xf bank_mask:0x5
	v_add_f32_dpp v104, v104, v104 row_ror:4 row_mask:0xf bank_mask:0xa
	v_add_f32_dpp v12, v12, v12 row_ror:8 row_mask:0xf bank_mask:0xf bound_ctrl:1
	v_pk_fma_f32 v[6:7], v[114:115], v[12:13], v[48:49] op_sel_hi:[1,0,1] neg_lo:[1,0,0] neg_hi:[1,0,0]
	v_pk_fma_f32 v[8:9], v[116:117], v[12:13], v[50:51] op_sel_hi:[1,0,1] neg_lo:[1,0,0] neg_hi:[1,0,0]
	v_pk_mul_f32 v[6:7], v[6:7], v[106:107]
	v_pk_mul_f32 v[8:9], v[8:9], v[108:109]
	s_waitcnt lgkmcnt(0)
	s_nop 0
	v_fma_mix_f32 v12, v6, v20, v180 op_sel_hi:[0,1,0]
	v_fma_mix_f32 v12, v7, v20, v12 op_sel:[0,1,0] op_sel_hi:[0,1,0]
	v_fma_mix_f32 v12, v8, v21, v12 op_sel_hi:[0,1,0]
	v_fma_mix_f32 v12, v9, v21, v12 op_sel:[0,1,0] op_sel_hi:[0,1,0]
	ds_read_b128 v[88:91], v10 offset:59648
	ds_read_b128 v[96:99], v10 offset:60160
	ds_read_b128 v[92:95], v10 offset:59904
	v_fma_mix_f32 v129, v6, v112, v180 op_sel_hi:[0,1,0]
	v_fma_mix_f32 v129, v7, v112, v129 op_sel:[0,1,0] op_sel_hi:[0,1,0]
	v_add_f32_dpp v12, v12, v12 row_ror:1 row_mask:0xf bank_mask:0xf bound_ctrl:1
	v_fma_mix_f32 v129, v8, v113, v129 op_sel_hi:[0,1,0]
	v_fma_mix_f32 v129, v9, v113, v129 op_sel:[0,1,0] op_sel_hi:[0,1,0]
	v_add_f32_dpp v12, v12, v12 row_ror:2 row_mask:0xf bank_mask:0xf bound_ctrl:1
	v_pk_fma_f32 v[48:49], v[28:29], v[66:67], v[6:7] op_sel_hi:[1,0,1]
	v_pk_fma_f32 v[50:51], v[30:31], v[66:67], v[8:9] op_sel_hi:[1,0,1]
	v_add_f32_dpp v12, v12, v12 row_ror:4 row_mask:0xf bank_mask:0xf bound_ctrl:1
	v_add_f32_dpp v104, v100, v100 row_ror:12 row_mask:0xf bank_mask:0x5
	v_add_f32_dpp v105, v105, v105 row_ror:4 row_mask:0xf bank_mask:0xa
	v_add_f32_dpp v105, v101, v101 row_ror:12 row_mask:0xf bank_mask:0x5
	v_add_f32_dpp v12, v12, v12 row_ror:8 row_mask:0xf bank_mask:0xf bound_ctrl:1
	v_pk_fma_f32 v[6:7], v[24:25], v[12:13], v[48:49] op_sel_hi:[1,0,1] neg_lo:[1,0,0] neg_hi:[1,0,0]
	v_pk_fma_f32 v[8:9], v[26:27], v[12:13], v[50:51] op_sel_hi:[1,0,1] neg_lo:[1,0,0] neg_hi:[1,0,0]
	v_fma_mix_f32 v12, v6, v36, v180 op_sel_hi:[0,1,0]
	v_fma_mix_f32 v12, v7, v36, v12 op_sel:[0,1,0] op_sel_hi:[0,1,0]
	v_fma_mix_f32 v12, v8, v37, v12 op_sel_hi:[0,1,0]
	v_fma_mix_f32 v12, v9, v37, v12 op_sel:[0,1,0] op_sel_hi:[0,1,0]
	ds_read_b128 v[110:113], v10 offset:60672
	ds_read_b128 v[106:109], v10 offset:60416
	ds_read_b128 v[118:121], v10 offset:61184
	ds_read_b128 v[114:117], v10 offset:60928
	ds_read_b128 v[70:73], v11 offset:3840
	v_fma_mix_f32 v130, v6, v22, v180 op_sel_hi:[0,1,0]
	v_fma_mix_f32 v130, v7, v22, v130 op_sel:[0,1,0] op_sel_hi:[0,1,0]
	v_add_f32_dpp v12, v12, v12 row_ror:1 row_mask:0xf bank_mask:0xf bound_ctrl:1
	v_fma_mix_f32 v130, v8, v23, v130 op_sel_hi:[0,1,0]
	v_fma_mix_f32 v130, v9, v23, v130 op_sel:[0,1,0] op_sel_hi:[0,1,0]
	v_add_f32_dpp v12, v12, v12 row_ror:2 row_mask:0xf bank_mask:0xf bound_ctrl:1
	v_pk_fma_f32 v[48:49], v[44:45], v[66:67], v[6:7] op_sel:[0,1,0]
	v_pk_fma_f32 v[50:51], v[46:47], v[66:67], v[8:9] op_sel:[0,1,0]
	v_add_f32_dpp v12, v12, v12 row_ror:4 row_mask:0xf bank_mask:0xf bound_ctrl:1
	v_add_f32_dpp v61, v61, v61 row_ror:4 row_mask:0xf bank_mask:0xa
	v_add_f32_dpp v61, v102, v102 row_ror:12 row_mask:0xf bank_mask:0x5
	v_add_f32_dpp v12, v12, v12 row_ror:8 row_mask:0xf bank_mask:0xf bound_ctrl:1
	v_pk_fma_f32 v[6:7], v[40:41], v[12:13], v[48:49] op_sel_hi:[1,0,1] neg_lo:[1,0,0] neg_hi:[1,0,0]
	v_pk_fma_f32 v[8:9], v[42:43], v[12:13], v[50:51] op_sel_hi:[1,0,1] neg_lo:[1,0,0] neg_hi:[1,0,0]
	s_waitcnt lgkmcnt(1)
	s_nop 0
	v_fma_mix_f32 v12, v6, v88, v180 op_sel_hi:[0,1,0]
	v_fma_mix_f32 v12, v7, v88, v12 op_sel:[0,1,0] op_sel_hi:[0,1,0]
	v_fma_mix_f32 v12, v8, v89, v12 op_sel_hi:[0,1,0]
	v_fma_mix_f32 v12, v9, v89, v12 op_sel:[0,1,0] op_sel_hi:[0,1,0]
	ds_read_b128 v[20:23], v10 offset:61696
	ds_read_b128 v[28:31], v10 offset:62208
	ds_read_b128 v[24:27], v10 offset:61952
	v_fma_mix_f32 v131, v6, v38, v180 op_sel_hi:[0,1,0]
	v_fma_mix_f32 v131, v7, v38, v131 op_sel:[0,1,0] op_sel_hi:[0,1,0]
	v_add_f32_dpp v12, v12, v12 row_ror:1 row_mask:0xf bank_mask:0xf bound_ctrl:1
	v_fma_mix_f32 v131, v8, v39, v131 op_sel_hi:[0,1,0]
	v_fma_mix_f32 v131, v9, v39, v131 op_sel:[0,1,0] op_sel_hi:[0,1,0]
	v_add_f32_dpp v12, v12, v12 row_ror:2 row_mask:0xf bank_mask:0xf bound_ctrl:1
	v_pk_fma_f32 v[48:49], v[96:97], v[68:69], v[6:7] op_sel_hi:[1,0,1]
	v_pk_fma_f32 v[50:51], v[98:99], v[68:69], v[8:9] op_sel_hi:[1,0,1]
	v_add_f32_dpp v12, v12, v12 row_ror:4 row_mask:0xf bank_mask:0xf bound_ctrl:1
	v_cndmask_b32_e64 v62, v105, v103, s[38:39]
	v_cndmask_b32_e64 v63, v103, v105, s[38:39]
	v_add_f32_dpp v12, v12, v12 row_ror:8 row_mask:0xf bank_mask:0xf bound_ctrl:1
	v_pk_fma_f32 v[6:7], v[92:93], v[12:13], v[48:49] op_sel_hi:[1,0,1] neg_lo:[1,0,0] neg_hi:[1,0,0]
	v_pk_fma_f32 v[8:9], v[94:95], v[12:13], v[50:51] op_sel_hi:[1,0,1] neg_lo:[1,0,0] neg_hi:[1,0,0]
	v_fma_mix_f32 v12, v6, v110, v180 op_sel_hi:[0,1,0]
	v_fma_mix_f32 v12, v7, v110, v12 op_sel:[0,1,0] op_sel_hi:[0,1,0]
	v_fma_mix_f32 v12, v8, v111, v12 op_sel_hi:[0,1,0]
	v_fma_mix_f32 v12, v9, v111, v12 op_sel:[0,1,0] op_sel_hi:[0,1,0]
	ds_read_b128 v[36:39], v10 offset:62720
	ds_read_b128 v[44:47], v10 offset:63232
	ds_read_b128 v[40:43], v10 offset:62976
	v_fma_mix_f32 v132, v6, v90, v180 op_sel_hi:[0,1,0]
	v_fma_mix_f32 v132, v7, v90, v132 op_sel:[0,1,0] op_sel_hi:[0,1,0]
	v_add_f32_dpp v12, v12, v12 row_ror:1 row_mask:0xf bank_mask:0xf bound_ctrl:1
	v_fma_mix_f32 v132, v8, v91, v132 op_sel_hi:[0,1,0]
	v_fma_mix_f32 v132, v9, v91, v132 op_sel:[0,1,0] op_sel_hi:[0,1,0]
	v_add_f32_dpp v12, v12, v12 row_ror:2 row_mask:0xf bank_mask:0xf bound_ctrl:1
	v_pk_fma_f32 v[48:49], v[118:119], v[68:69], v[6:7] op_sel:[0,1,0]
	v_pk_fma_f32 v[50:51], v[120:121], v[68:69], v[8:9] op_sel:[0,1,0]
	v_add_f32_dpp v12, v12, v12 row_ror:4 row_mask:0xf bank_mask:0xf bound_ctrl:1
	v_cndmask_b32_e64 v64, v61, v104, s[38:39]
	v_cndmask_b32_e64 v65, v104, v61, s[38:39]
	v_add_f32_dpp v12, v12, v12 row_ror:8 row_mask:0xf bank_mask:0xf bound_ctrl:1
	v_pk_fma_f32 v[6:7], v[114:115], v[12:13], v[48:49] op_sel_hi:[1,0,1] neg_lo:[1,0,0] neg_hi:[1,0,0]
	v_pk_fma_f32 v[8:9], v[116:117], v[12:13], v[50:51] op_sel_hi:[1,0,1] neg_lo:[1,0,0] neg_hi:[1,0,0]
	v_pk_mul_f32 v[6:7], v[6:7], v[106:107]
	v_pk_mul_f32 v[8:9], v[8:9], v[108:109]
	s_waitcnt lgkmcnt(0)
	s_nop 0
	v_fma_mix_f32 v12, v6, v20, v180 op_sel_hi:[0,1,0]
	v_fma_mix_f32 v12, v7, v20, v12 op_sel:[0,1,0] op_sel_hi:[0,1,0]
	v_fma_mix_f32 v12, v8, v21, v12 op_sel_hi:[0,1,0]
	v_fma_mix_f32 v12, v9, v21, v12 op_sel:[0,1,0] op_sel_hi:[0,1,0]
	ds_read_b128 v[88:91], v10 offset:63744
	ds_read_b128 v[96:99], v10 offset:64256
	ds_read_b128 v[92:95], v10 offset:64000
	v_fma_mix_f32 v133, v6, v112, v180 op_sel_hi:[0,1,0]
	v_fma_mix_f32 v133, v7, v112, v133 op_sel:[0,1,0] op_sel_hi:[0,1,0]
	v_add_f32_dpp v12, v12, v12 row_ror:1 row_mask:0xf bank_mask:0xf bound_ctrl:1
	v_fma_mix_f32 v133, v8, v113, v133 op_sel_hi:[0,1,0]
	v_fma_mix_f32 v133, v9, v113, v133 op_sel:[0,1,0] op_sel_hi:[0,1,0]
	v_add_f32_dpp v12, v12, v12 row_ror:2 row_mask:0xf bank_mask:0xf bound_ctrl:1
	v_pk_fma_f32 v[48:49], v[28:29], v[70:71], v[6:7] op_sel_hi:[1,0,1]
	v_pk_fma_f32 v[50:51], v[30:31], v[70:71], v[8:9] op_sel_hi:[1,0,1]
	v_add_f32_dpp v12, v12, v12 row_ror:4 row_mask:0xf bank_mask:0xf bound_ctrl:1
	v_add_f32_dpp v62, v63, v62 quad_perm:[2,3,0,1] row_mask:0xf bank_mask:0xf bound_ctrl:1
	v_add_f32_dpp v63, v65, v64 quad_perm:[2,3,0,1] row_mask:0xf bank_mask:0xf bound_ctrl:1
	v_add_f32_dpp v12, v12, v12 row_ror:8 row_mask:0xf bank_mask:0xf bound_ctrl:1
	v_pk_fma_f32 v[6:7], v[24:25], v[12:13], v[48:49] op_sel_hi:[1,0,1] neg_lo:[1,0,0] neg_hi:[1,0,0]
	v_pk_fma_f32 v[8:9], v[26:27], v[12:13], v[50:51] op_sel_hi:[1,0,1] neg_lo:[1,0,0] neg_hi:[1,0,0]
	v_fma_mix_f32 v12, v6, v36, v180 op_sel_hi:[0,1,0]
	v_fma_mix_f32 v12, v7, v36, v12 op_sel:[0,1,0] op_sel_hi:[0,1,0]
	v_fma_mix_f32 v12, v8, v37, v12 op_sel_hi:[0,1,0]
	v_fma_mix_f32 v12, v9, v37, v12 op_sel:[0,1,0] op_sel_hi:[0,1,0]
	ds_read_b128 v[110:113], v10 offset:64768
	ds_read_b128 v[106:109], v10 offset:64512
	ds_read_b128 v[118:121], v10 offset:65280
	ds_read_b128 v[114:117], v10 offset:65024
	v_fma_mix_f32 v134, v6, v22, v180 op_sel_hi:[0,1,0]
	v_fma_mix_f32 v134, v7, v22, v134 op_sel:[0,1,0] op_sel_hi:[0,1,0]
	v_add_f32_dpp v12, v12, v12 row_ror:1 row_mask:0xf bank_mask:0xf bound_ctrl:1
	v_fma_mix_f32 v134, v8, v23, v134 op_sel_hi:[0,1,0]
	v_fma_mix_f32 v134, v9, v23, v134 op_sel:[0,1,0] op_sel_hi:[0,1,0]
	v_add_f32_dpp v12, v12, v12 row_ror:2 row_mask:0xf bank_mask:0xf bound_ctrl:1
	v_pk_fma_f32 v[48:49], v[44:45], v[70:71], v[6:7] op_sel:[0,1,0]
	v_pk_fma_f32 v[50:51], v[46:47], v[70:71], v[8:9] op_sel:[0,1,0]
	v_add_f32_dpp v12, v12, v12 row_ror:4 row_mask:0xf bank_mask:0xf bound_ctrl:1
	v_cndmask_b32_e64 v65, v63, v62, s[40:41]
	v_cndmask_b32_e64 v62, v62, v63, s[40:41]
	v_add_f32_dpp v12, v12, v12 row_ror:8 row_mask:0xf bank_mask:0xf bound_ctrl:1
	v_pk_fma_f32 v[6:7], v[40:41], v[12:13], v[48:49] op_sel_hi:[1,0,1] neg_lo:[1,0,0] neg_hi:[1,0,0]
	v_pk_fma_f32 v[8:9], v[42:43], v[12:13], v[50:51] op_sel_hi:[1,0,1] neg_lo:[1,0,0] neg_hi:[1,0,0]
	s_waitcnt lgkmcnt(0)
	s_nop 0
	v_fma_mix_f32 v12, v6, v88, v180 op_sel_hi:[0,1,0]
	v_fma_mix_f32 v12, v7, v88, v12 op_sel:[0,1,0] op_sel_hi:[0,1,0]
	v_fma_mix_f32 v12, v8, v89, v12 op_sel_hi:[0,1,0]
	v_fma_mix_f32 v12, v9, v89, v12 op_sel:[0,1,0] op_sel_hi:[0,1,0]
	v_fma_mix_f32 v135, v6, v38, v180 op_sel_hi:[0,1,0]
	v_fma_mix_f32 v135, v7, v38, v135 op_sel:[0,1,0] op_sel_hi:[0,1,0]
	v_add_f32_dpp v12, v12, v12 row_ror:1 row_mask:0xf bank_mask:0xf bound_ctrl:1
	v_fma_mix_f32 v135, v8, v39, v135 op_sel_hi:[0,1,0]
	v_fma_mix_f32 v135, v9, v39, v135 op_sel:[0,1,0] op_sel_hi:[0,1,0]
	v_add_f32_dpp v12, v12, v12 row_ror:2 row_mask:0xf bank_mask:0xf bound_ctrl:1
	v_pk_fma_f32 v[48:49], v[96:97], v[72:73], v[6:7] op_sel_hi:[1,0,1]
	v_pk_fma_f32 v[50:51], v[98:99], v[72:73], v[8:9] op_sel_hi:[1,0,1]
	v_add_f32_dpp v12, v12, v12 row_ror:4 row_mask:0xf bank_mask:0xf bound_ctrl:1
	v_add_f32_dpp v62, v62, v65 quad_perm:[1,0,3,2] row_mask:0xf bank_mask:0xf bound_ctrl:1
	v_cvt_pk_bf16_f32 v62, v62, v62
	v_add_f32_dpp v12, v12, v12 row_ror:8 row_mask:0xf bank_mask:0xf bound_ctrl:1
	v_pk_fma_f32 v[6:7], v[92:93], v[12:13], v[48:49] op_sel_hi:[1,0,1] neg_lo:[1,0,0] neg_hi:[1,0,0]
	v_pk_fma_f32 v[8:9], v[94:95], v[12:13], v[50:51] op_sel_hi:[1,0,1] neg_lo:[1,0,0] neg_hi:[1,0,0]
	s_waitcnt lgkmcnt(0)
	s_barrier
	v_xor_b32_e32 v10, 0x10000, v10
	v_xor_b32_e32 v11, 0x1000, v11
	ds_read_b128 v[66:69], v11 offset:0
	ds_read_b128 v[20:23], v10 offset:256
	ds_read_b128 v[28:31], v10 offset:768
	ds_read_b128 v[24:27], v10 offset:512
	ds_read_b128 v[36:39], v10 offset:1280
	ds_read_b128 v[44:47], v10 offset:1792
	ds_read_b128 v[40:43], v10 offset:1536
	v_fma_mix_f32 v12, v6, v110, v180 op_sel_hi:[0,1,0]
	v_fma_mix_f32 v12, v7, v110, v12 op_sel:[0,1,0] op_sel_hi:[0,1,0]
	v_fma_mix_f32 v12, v8, v111, v12 op_sel_hi:[0,1,0]
	v_fma_mix_f32 v12, v9, v111, v12 op_sel:[0,1,0] op_sel_hi:[0,1,0]
	v_fma_mix_f32 v136, v6, v90, v180 op_sel_hi:[0,1,0]
	v_fma_mix_f32 v136, v7, v90, v136 op_sel:[0,1,0] op_sel_hi:[0,1,0]
	v_add_f32_dpp v12, v12, v12 row_ror:1 row_mask:0xf bank_mask:0xf bound_ctrl:1
	v_fma_mix_f32 v136, v8, v91, v136 op_sel_hi:[0,1,0]
	v_fma_mix_f32 v136, v9, v91, v136 op_sel:[0,1,0] op_sel_hi:[0,1,0]
	v_add_f32_dpp v12, v12, v12 row_ror:2 row_mask:0xf bank_mask:0xf bound_ctrl:1
	v_pk_fma_f32 v[48:49], v[118:119], v[72:73], v[6:7] op_sel:[0,1,0]
	v_pk_fma_f32 v[50:51], v[120:121], v[72:73], v[8:9] op_sel:[0,1,0]
	v_add_f32_dpp v12, v12, v12 row_ror:4 row_mask:0xf bank_mask:0xf bound_ctrl:1
	global_store_short v[2:3], v62, off
	v_lshl_add_u64 v[2:3], v[2:3], 0, s[84:85]
	v_add_f32_dpp v12, v12, v12 row_ror:8 row_mask:0xf bank_mask:0xf bound_ctrl:1
	v_pk_fma_f32 v[6:7], v[114:115], v[12:13], v[48:49] op_sel_hi:[1,0,1] neg_lo:[1,0,0] neg_hi:[1,0,0]
	v_pk_fma_f32 v[8:9], v[116:117], v[12:13], v[50:51] op_sel_hi:[1,0,1] neg_lo:[1,0,0] neg_hi:[1,0,0]
	v_pk_mul_f32 v[6:7], v[6:7], v[106:107]
	v_pk_mul_f32 v[8:9], v[8:9], v[108:109]
	v_fma_mix_f32 v137, v6, v112, v180 op_sel_hi:[0,1,0]
	v_fma_mix_f32 v137, v7, v112, v137 op_sel:[0,1,0] op_sel_hi:[0,1,0]
	v_fma_mix_f32 v137, v8, v113, v137 op_sel_hi:[0,1,0]
	v_fma_mix_f32 v137, v9, v113, v137 op_sel:[0,1,0] op_sel_hi:[0,1,0]
	v_mov_b32_e64 v170, v2
	v_mov_b32_e64 v171, v3
	s_mov_b64 s[100:101], -1
	s_nop 0
	s_cmp_lg_u32 s28, 0x800000
	s_cbranch_scc1 .Lscan_cons_chunk
	v_add_f32_dpp v130, v130, v130 row_ror:8 row_mask:0xf bank_mask:0xc
	v_add_f32_dpp v130, v122, v122 row_ror:8 row_mask:0xf bank_mask:0x3
	v_add_f32_dpp v131, v131, v131 row_ror:8 row_mask:0xf bank_mask:0xc
	v_add_f32_dpp v131, v123, v123 row_ror:8 row_mask:0xf bank_mask:0x3
	v_add_f32_dpp v132, v132, v132 row_ror:8 row_mask:0xf bank_mask:0xc
	v_add_f32_dpp v132, v124, v124 row_ror:8 row_mask:0xf bank_mask:0x3
	v_add_f32_dpp v133, v133, v133 row_ror:8 row_mask:0xf bank_mask:0xc
	v_add_f32_dpp v133, v125, v125 row_ror:8 row_mask:0xf bank_mask:0x3
	v_add_f32_dpp v134, v134, v134 row_ror:8 row_mask:0xf bank_mask:0xc
	v_add_f32_dpp v134, v126, v126 row_ror:8 row_mask:0xf bank_mask:0x3
	v_add_f32_dpp v135, v135, v135 row_ror:8 row_mask:0xf bank_mask:0xc
	v_add_f32_dpp v135, v127, v127 row_ror:8 row_mask:0xf bank_mask:0x3
	v_add_f32_dpp v136, v136, v136 row_ror:8 row_mask:0xf bank_mask:0xc
	v_add_f32_dpp v136, v128, v128 row_ror:8 row_mask:0xf bank_mask:0x3
	v_add_f32_dpp v137, v137, v137 row_ror:8 row_mask:0xf bank_mask:0xc
	v_add_f32_dpp v137, v129, v129 row_ror:8 row_mask:0xf bank_mask:0x3
	v_add_f32_dpp v134, v134, v134 row_ror:4 row_mask:0xf bank_mask:0xa
	v_add_f32_dpp v134, v130, v130 row_ror:12 row_mask:0xf bank_mask:0x5
	v_add_f32_dpp v135, v135, v135 row_ror:4 row_mask:0xf bank_mask:0xa
	v_add_f32_dpp v135, v131, v131 row_ror:12 row_mask:0xf bank_mask:0x5
	v_add_f32_dpp v136, v136, v136 row_ror:4 row_mask:0xf bank_mask:0xa
	v_add_f32_dpp v136, v132, v132 row_ror:12 row_mask:0xf bank_mask:0x5
	v_add_f32_dpp v137, v137, v137 row_ror:4 row_mask:0xf bank_mask:0xa
	v_add_f32_dpp v137, v133, v133 row_ror:12 row_mask:0xf bank_mask:0x5
	v_cndmask_b32_e64 v62, v136, v134, s[38:39]
	v_cndmask_b32_e64 v63, v134, v136, s[38:39]
	v_cndmask_b32_e64 v64, v137, v135, s[38:39]
	v_cndmask_b32_e64 v65, v135, v137, s[38:39]
	v_add_f32_dpp v62, v63, v62 quad_perm:[2,3,0,1] row_mask:0xf bank_mask:0xf bound_ctrl:1
	s_nop 0
	v_add_f32_dpp v63, v65, v64 quad_perm:[2,3,0,1] row_mask:0xf bank_mask:0xf bound_ctrl:1
	v_cndmask_b32_e64 v65, v63, v62, s[40:41]
	v_cndmask_b32_e64 v62, v62, v63, s[40:41]
	s_nop 1
	v_add_f32_dpp v62, v62, v65 quad_perm:[1,0,3,2] row_mask:0xf bank_mask:0xf bound_ctrl:1
	v_cvt_pk_bf16_f32 v62, v62, v62
	global_store_short v[2:3], v62, off
	s_branch .LBB0_53
